# v18: v17 + s_nop before LDS-DMA removed (address VALU placed between m0 write and load)
# baseline (speedup 1.0000x reference)
.LBB0_271:
	s_add_u32 s26, s14, 0xfffc0080
	s_addc_u32 s27, s15, -1
	s_add_i32 s54, 0, 0x10000
	s_cmp_eq_u32 s53, 12
	s_cselect_b32 s29, s21, s27
	s_cselect_b32 s28, s49, s26
	v_add_u32_e32 v154, s54, v141
	s_cselect_b32 s27, s19, s52
	s_cselect_b32 s26, s50, s51
	s_add_i32 s56, 0, 0x14000
	ds_read_b128 v[146:149], v154
	ds_read_b128 v[150:153], v154 offset:1024
	ds_read_b128 v[162:165], v154 offset:2048
	ds_read_b128 v[166:169], v154 offset:3072
	v_add_u32_e32 v154, s56, v141
	ds_read_b128 v[170:173], v154
	ds_read_b128 v[186:189], v154 offset:1024
	ds_read_b128 v[190:193], v154 offset:2048
	ds_read_b128 v[194:197], v154 offset:3072
	v_lshl_add_u64 v[154:155], s[14:15], 0, v[136:137]
	s_add_i32 m0, s37, 0xc000
	ds_read_b128 v[198:201], v145
	ds_read_b128 v[202:205], v145 offset:1024
	ds_read_b128 v[206:209], v145 offset:2048
	ds_read_b128 v[210:213], v145 offset:3072
	ds_read_b128 v[214:217], v145 offset:4096
	ds_read_b128 v[218:221], v145 offset:5120
	ds_read_b128 v[222:225], v145 offset:6144
	ds_read_b128 v[226:229], v145 offset:7168
	global_load_lds_dwordx4 v[154:155], off
	s_add_i32 m0, s37, 0xe000
	v_lshl_add_u64 v[154:155], s[14:15], 0, v[138:139]
	global_load_lds_dwordx4 v[154:155], off
	s_setprio 1
	s_waitcnt vmcnt(8) lgkmcnt(0)
	s_barrier
	v_mfma_f32_16x16x32_bf16 v[126:129], v[146:149], v[198:201], v[126:129]
	v_mfma_f32_16x16x32_bf16 v[122:125], v[162:165], v[198:201], v[122:125]
	v_mfma_f32_16x16x32_bf16 v[110:113], v[146:149], v[206:209], v[110:113]
	v_mfma_f32_16x16x32_bf16 v[106:109], v[162:165], v[206:209], v[106:109]
	v_mfma_f32_16x16x32_bf16 v[92:95], v[146:149], v[214:217], v[92:95]
	v_mfma_f32_16x16x32_bf16 v[88:91], v[162:165], v[214:217], v[88:91]
	v_mfma_f32_16x16x32_bf16 v[76:79], v[146:149], v[222:225], v[76:79]
	v_mfma_f32_16x16x32_bf16 v[72:75], v[162:165], v[222:225], v[72:75]
	v_mfma_f32_16x16x32_bf16 v[126:129], v[150:153], v[202:205], v[126:129]
	v_mfma_f32_16x16x32_bf16 v[122:125], v[166:169], v[202:205], v[122:125]
	v_mfma_f32_16x16x32_bf16 v[110:113], v[150:153], v[210:213], v[110:113]
	v_mfma_f32_16x16x32_bf16 v[106:109], v[166:169], v[210:213], v[106:109]
	v_mfma_f32_16x16x32_bf16 v[92:95], v[150:153], v[218:221], v[92:95]
	v_mfma_f32_16x16x32_bf16 v[88:91], v[166:169], v[218:221], v[88:91]
	v_mfma_f32_16x16x32_bf16 v[76:79], v[150:153], v[226:229], v[76:79]
	v_mfma_f32_16x16x32_bf16 v[72:75], v[166:169], v[226:229], v[72:75]
	s_setprio 0
	s_setprio 1
	v_mfma_f32_16x16x32_bf16 v[118:121], v[170:173], v[198:201], v[118:121]
	v_mfma_f32_16x16x32_bf16 v[114:117], v[190:193], v[198:201], v[114:117]
	v_mfma_f32_16x16x32_bf16 v[102:105], v[170:173], v[206:209], v[102:105]
	v_mfma_f32_16x16x32_bf16 v[98:101], v[190:193], v[206:209], v[98:101]
	v_mfma_f32_16x16x32_bf16 v[84:87], v[170:173], v[214:217], v[84:87]
	v_mfma_f32_16x16x32_bf16 v[80:83], v[190:193], v[214:217], v[80:83]
	v_mfma_f32_16x16x32_bf16 v[68:71], v[170:173], v[222:225], v[68:71]
	v_mfma_f32_16x16x32_bf16 v[64:67], v[190:193], v[222:225], v[64:67]
	v_mfma_f32_16x16x32_bf16 v[118:121], v[186:189], v[202:205], v[118:121]
	v_mfma_f32_16x16x32_bf16 v[114:117], v[194:197], v[202:205], v[114:117]
	v_mfma_f32_16x16x32_bf16 v[102:105], v[186:189], v[210:213], v[102:105]
	v_mfma_f32_16x16x32_bf16 v[98:101], v[194:197], v[210:213], v[98:101]
	v_mfma_f32_16x16x32_bf16 v[84:87], v[186:189], v[218:221], v[84:87]
	v_mfma_f32_16x16x32_bf16 v[80:83], v[194:197], v[218:221], v[80:83]
	v_mfma_f32_16x16x32_bf16 v[68:71], v[186:189], v[226:229], v[68:71]
	v_mfma_f32_16x16x32_bf16 v[64:67], v[194:197], v[226:229], v[64:67]
	s_setprio 2
	s_barrier
	s_add_i32 s54, s54, s36
	v_lshl_add_u64 v[154:155], s[26:27], 0, v[96:97]
	s_mov_b32 m0, s54
	ds_read_b128 v[198:201], v145 offset:16384
	ds_read_b128 v[202:205], v145 offset:17408
	ds_read_b128 v[206:209], v145 offset:18432
	ds_read_b128 v[210:213], v145 offset:19456
	ds_read_b128 v[214:217], v145 offset:20480
	ds_read_b128 v[218:221], v145 offset:21504
	ds_read_b128 v[222:225], v145 offset:22528
	ds_read_b128 v[226:229], v145 offset:23552
	global_load_lds_dwordx4 v[154:155], off
	s_add_i32 m0, s54, 0x2000
	s_add_u32 s54, s26, 0x40000
	v_lshl_add_u64 v[156:157], s[26:27], 0, v[130:131]
	s_addc_u32 s55, s27, 0
	s_add_i32 s56, s56, s36
	global_load_lds_dwordx4 v[156:157], off
	v_lshl_add_u64 v[158:159], s[54:55], 0, v[96:97]
	s_mov_b32 m0, s56
	v_lshl_add_u64 v[182:183], s[28:29], 0, v[132:133]
	global_load_lds_dwordx4 v[158:159], off
	s_add_i32 m0, s56, 0x2000
	v_lshl_add_u64 v[158:159], s[54:55], 0, v[130:131]
	global_load_lds_dwordx4 v[158:159], off
	s_mov_b32 m0, s37
	v_lshl_add_u64 v[158:159], s[28:29], 0, v[134:135]
	global_load_lds_dwordx4 v[158:159], off
	s_mov_b32 m0, s38
	s_nop 0
	global_load_lds_dwordx4 v[182:183], off
	s_setprio 1
	s_waitcnt vmcnt(8) lgkmcnt(0)
	s_barrier
	v_mfma_f32_16x16x32_bf16 v[60:63], v[146:149], v[198:201], v[60:63]
	v_mfma_f32_16x16x32_bf16 v[56:59], v[162:165], v[198:201], v[56:59]
	v_mfma_f32_16x16x32_bf16 v[44:47], v[146:149], v[206:209], v[44:47]
	v_mfma_f32_16x16x32_bf16 v[40:43], v[162:165], v[206:209], v[40:43]
	v_mfma_f32_16x16x32_bf16 v[28:31], v[146:149], v[214:217], v[28:31]
	v_mfma_f32_16x16x32_bf16 v[24:27], v[162:165], v[214:217], v[24:27]
	v_mfma_f32_16x16x32_bf16 v[12:15], v[146:149], v[222:225], v[12:15]
	v_mfma_f32_16x16x32_bf16 v[4:7], v[162:165], v[222:225], v[4:7]
	v_mfma_f32_16x16x32_bf16 v[60:63], v[150:153], v[202:205], v[60:63]
	v_mfma_f32_16x16x32_bf16 v[56:59], v[166:169], v[202:205], v[56:59]
	v_mfma_f32_16x16x32_bf16 v[44:47], v[150:153], v[210:213], v[44:47]
	v_mfma_f32_16x16x32_bf16 v[40:43], v[166:169], v[210:213], v[40:43]
	v_mfma_f32_16x16x32_bf16 v[28:31], v[150:153], v[218:221], v[28:31]
	v_mfma_f32_16x16x32_bf16 v[24:27], v[166:169], v[218:221], v[24:27]
	v_mfma_f32_16x16x32_bf16 v[12:15], v[150:153], v[226:229], v[12:15]
	v_mfma_f32_16x16x32_bf16 v[4:7], v[166:169], v[226:229], v[4:7]
	s_setprio 0
	s_setprio 1
	v_mfma_f32_16x16x32_bf16 v[52:55], v[170:173], v[198:201], v[52:55]
	v_mfma_f32_16x16x32_bf16 v[48:51], v[190:193], v[198:201], v[48:51]
	v_mfma_f32_16x16x32_bf16 v[36:39], v[170:173], v[206:209], v[36:39]
	v_mfma_f32_16x16x32_bf16 v[32:35], v[190:193], v[206:209], v[32:35]
	v_mfma_f32_16x16x32_bf16 v[20:23], v[170:173], v[214:217], v[20:23]
	v_mfma_f32_16x16x32_bf16 v[16:19], v[190:193], v[214:217], v[16:19]
	v_mfma_f32_16x16x32_bf16 v[8:11], v[170:173], v[222:225], v[8:11]
	v_mfma_f32_16x16x32_bf16 v[0:3], v[190:193], v[222:225], v[0:3]
	v_mfma_f32_16x16x32_bf16 v[52:55], v[186:189], v[202:205], v[52:55]
	v_mfma_f32_16x16x32_bf16 v[48:51], v[194:197], v[202:205], v[48:51]
	v_mfma_f32_16x16x32_bf16 v[36:39], v[186:189], v[210:213], v[36:39]
	v_mfma_f32_16x16x32_bf16 v[32:35], v[194:197], v[210:213], v[32:35]
	v_mfma_f32_16x16x32_bf16 v[20:23], v[186:189], v[218:221], v[20:23]
	v_mfma_f32_16x16x32_bf16 v[16:19], v[194:197], v[218:221], v[16:19]
	v_mfma_f32_16x16x32_bf16 v[8:11], v[186:189], v[226:229], v[8:11]
	v_mfma_f32_16x16x32_bf16 v[0:3], v[194:197], v[226:229], v[0:3]
	s_setprio 2
	s_barrier
	s_add_i32 s54, 0, 0x18000
	s_add_i32 s55, 0, 0x1c000
	v_add_u32_e32 v166, s54, v141
	v_add_u32_e32 v184, s55, v141
	ds_read_b128 v[146:149], v166
	ds_read_b128 v[150:153], v166 offset:1024
	ds_read_b128 v[162:165], v166 offset:2048
	ds_read_b128 v[166:169], v166 offset:3072
	ds_read_b128 v[170:173], v184
	ds_read_b128 v[186:189], v184 offset:1024
	ds_read_b128 v[190:193], v184 offset:2048
	ds_read_b128 v[194:197], v184 offset:3072
	s_add_u32 s28, s28, 0x40000
	s_addc_u32 s29, s29, 0
	s_mov_b32 m0, s39
	v_lshl_add_u64 v[184:185], s[28:29], 0, v[134:135]
	ds_read_b128 v[198:201], v145 offset:32768
	ds_read_b128 v[202:205], v145 offset:33792
	ds_read_b128 v[206:209], v145 offset:34816
	ds_read_b128 v[210:213], v145 offset:35840
	ds_read_b128 v[214:217], v145 offset:36864
	ds_read_b128 v[218:221], v145 offset:37888
	ds_read_b128 v[222:225], v145 offset:38912
	ds_read_b128 v[226:229], v145 offset:39936
	global_load_lds_dwordx4 v[184:185], off
	s_mov_b32 m0, s40
	v_lshl_add_u64 v[184:185], s[28:29], 0, v[132:133]
	global_load_lds_dwordx4 v[184:185], off
	s_setprio 1
	s_waitcnt vmcnt(8) lgkmcnt(0)
	s_barrier
	v_mfma_f32_16x16x32_bf16 v[126:129], v[146:149], v[198:201], v[126:129]
	v_mfma_f32_16x16x32_bf16 v[122:125], v[162:165], v[198:201], v[122:125]
	v_mfma_f32_16x16x32_bf16 v[110:113], v[146:149], v[206:209], v[110:113]
	v_mfma_f32_16x16x32_bf16 v[106:109], v[162:165], v[206:209], v[106:109]
	v_mfma_f32_16x16x32_bf16 v[92:95], v[146:149], v[214:217], v[92:95]
	v_mfma_f32_16x16x32_bf16 v[88:91], v[162:165], v[214:217], v[88:91]
	v_mfma_f32_16x16x32_bf16 v[76:79], v[146:149], v[222:225], v[76:79]
	v_mfma_f32_16x16x32_bf16 v[72:75], v[162:165], v[222:225], v[72:75]
	v_mfma_f32_16x16x32_bf16 v[126:129], v[150:153], v[202:205], v[126:129]
	v_mfma_f32_16x16x32_bf16 v[122:125], v[166:169], v[202:205], v[122:125]
	v_mfma_f32_16x16x32_bf16 v[110:113], v[150:153], v[210:213], v[110:113]
	v_mfma_f32_16x16x32_bf16 v[106:109], v[166:169], v[210:213], v[106:109]
	v_mfma_f32_16x16x32_bf16 v[92:95], v[150:153], v[218:221], v[92:95]
	v_mfma_f32_16x16x32_bf16 v[88:91], v[166:169], v[218:221], v[88:91]
	v_mfma_f32_16x16x32_bf16 v[76:79], v[150:153], v[226:229], v[76:79]
	v_mfma_f32_16x16x32_bf16 v[72:75], v[166:169], v[226:229], v[72:75]
	s_setprio 0
	s_setprio 1
	v_mfma_f32_16x16x32_bf16 v[118:121], v[170:173], v[198:201], v[118:121]
	v_mfma_f32_16x16x32_bf16 v[114:117], v[190:193], v[198:201], v[114:117]
	v_mfma_f32_16x16x32_bf16 v[102:105], v[170:173], v[206:209], v[102:105]
	v_mfma_f32_16x16x32_bf16 v[98:101], v[190:193], v[206:209], v[98:101]
	v_mfma_f32_16x16x32_bf16 v[84:87], v[170:173], v[214:217], v[84:87]
	v_mfma_f32_16x16x32_bf16 v[80:83], v[190:193], v[214:217], v[80:83]
	v_mfma_f32_16x16x32_bf16 v[68:71], v[170:173], v[222:225], v[68:71]
	v_mfma_f32_16x16x32_bf16 v[64:67], v[190:193], v[222:225], v[64:67]
	v_mfma_f32_16x16x32_bf16 v[118:121], v[186:189], v[202:205], v[118:121]
	v_mfma_f32_16x16x32_bf16 v[114:117], v[194:197], v[202:205], v[114:117]
	v_mfma_f32_16x16x32_bf16 v[102:105], v[186:189], v[210:213], v[102:105]
	v_mfma_f32_16x16x32_bf16 v[98:101], v[194:197], v[210:213], v[98:101]
	v_mfma_f32_16x16x32_bf16 v[84:87], v[186:189], v[218:221], v[84:87]
	v_mfma_f32_16x16x32_bf16 v[80:83], v[194:197], v[218:221], v[80:83]
	v_mfma_f32_16x16x32_bf16 v[68:71], v[186:189], v[226:229], v[68:71]
	v_mfma_f32_16x16x32_bf16 v[64:67], v[194:197], v[226:229], v[64:67]
	s_setprio 2
	s_barrier
	s_add_i32 s28, s54, s36
	v_lshl_add_u64 v[154:155], v[154:155], 0, s[16:17]
	s_mov_b32 m0, s28
	ds_read_b128 v[198:201], v145 offset:49152
	ds_read_b128 v[202:205], v145 offset:50176
	ds_read_b128 v[206:209], v145 offset:51200
	ds_read_b128 v[210:213], v145 offset:52224
	ds_read_b128 v[214:217], v145 offset:53248
	ds_read_b128 v[218:221], v145 offset:54272
	ds_read_b128 v[222:225], v145 offset:55296
	ds_read_b128 v[226:229], v145 offset:56320
	global_load_lds_dwordx4 v[154:155], off
	s_add_i32 m0, s28, 0x2000
	s_add_u32 s26, s26, 0x40080
	v_lshl_add_u64 v[154:155], v[156:157], 0, s[16:17]
	s_addc_u32 s27, s27, 0
	s_add_i32 s28, s55, s36
	global_load_lds_dwordx4 v[154:155], off
	s_mov_b32 m0, s28
	v_lshl_add_u64 v[154:155], s[26:27], 0, v[96:97]
	global_load_lds_dwordx4 v[154:155], off
	s_add_i32 m0, s28, 0x2000
	v_lshl_add_u64 v[154:155], s[26:27], 0, v[130:131]
	global_load_lds_dwordx4 v[154:155], off
	s_mov_b32 m0, s41
	v_lshl_add_u64 v[154:155], v[158:159], 0, s[16:17]
	global_load_lds_dwordx4 v[154:155], off
	s_mov_b32 m0, s42
	v_lshl_add_u64 v[154:155], v[182:183], 0, s[16:17]
	global_load_lds_dwordx4 v[154:155], off
	s_setprio 1
	s_waitcnt vmcnt(8) lgkmcnt(0)
	s_barrier
	v_mfma_f32_16x16x32_bf16 v[60:63], v[146:149], v[198:201], v[60:63]
	v_mfma_f32_16x16x32_bf16 v[56:59], v[162:165], v[198:201], v[56:59]
	v_mfma_f32_16x16x32_bf16 v[44:47], v[146:149], v[206:209], v[44:47]
	v_mfma_f32_16x16x32_bf16 v[40:43], v[162:165], v[206:209], v[40:43]
	v_mfma_f32_16x16x32_bf16 v[28:31], v[146:149], v[214:217], v[28:31]
	v_mfma_f32_16x16x32_bf16 v[24:27], v[162:165], v[214:217], v[24:27]
	v_mfma_f32_16x16x32_bf16 v[12:15], v[146:149], v[222:225], v[12:15]
	v_mfma_f32_16x16x32_bf16 v[4:7], v[162:165], v[222:225], v[4:7]
	v_mfma_f32_16x16x32_bf16 v[60:63], v[150:153], v[202:205], v[60:63]
	v_mfma_f32_16x16x32_bf16 v[56:59], v[166:169], v[202:205], v[56:59]
	v_mfma_f32_16x16x32_bf16 v[44:47], v[150:153], v[210:213], v[44:47]
	v_mfma_f32_16x16x32_bf16 v[40:43], v[166:169], v[210:213], v[40:43]
	v_mfma_f32_16x16x32_bf16 v[28:31], v[150:153], v[218:221], v[28:31]
	v_mfma_f32_16x16x32_bf16 v[24:27], v[166:169], v[218:221], v[24:27]
	v_mfma_f32_16x16x32_bf16 v[12:15], v[150:153], v[226:229], v[12:15]
	v_mfma_f32_16x16x32_bf16 v[4:7], v[166:169], v[226:229], v[4:7]
	s_setprio 0
	s_setprio 1
	v_mfma_f32_16x16x32_bf16 v[52:55], v[170:173], v[198:201], v[52:55]
	v_mfma_f32_16x16x32_bf16 v[48:51], v[190:193], v[198:201], v[48:51]
	v_mfma_f32_16x16x32_bf16 v[36:39], v[170:173], v[206:209], v[36:39]
	v_mfma_f32_16x16x32_bf16 v[32:35], v[190:193], v[206:209], v[32:35]
	v_mfma_f32_16x16x32_bf16 v[20:23], v[170:173], v[214:217], v[20:23]
	v_mfma_f32_16x16x32_bf16 v[16:19], v[190:193], v[214:217], v[16:19]
	v_mfma_f32_16x16x32_bf16 v[8:11], v[170:173], v[222:225], v[8:11]
	v_mfma_f32_16x16x32_bf16 v[0:3], v[190:193], v[222:225], v[0:3]
	v_mfma_f32_16x16x32_bf16 v[52:55], v[186:189], v[202:205], v[52:55]
	v_mfma_f32_16x16x32_bf16 v[48:51], v[194:197], v[202:205], v[48:51]
	v_mfma_f32_16x16x32_bf16 v[36:39], v[186:189], v[210:213], v[36:39]
	v_mfma_f32_16x16x32_bf16 v[32:35], v[194:197], v[210:213], v[32:35]
	v_mfma_f32_16x16x32_bf16 v[20:23], v[186:189], v[218:221], v[20:23]
	v_mfma_f32_16x16x32_bf16 v[16:19], v[194:197], v[218:221], v[16:19]
	v_mfma_f32_16x16x32_bf16 v[8:11], v[186:189], v[226:229], v[8:11]
	v_mfma_f32_16x16x32_bf16 v[0:3], v[194:197], v[226:229], v[0:3]
	s_setprio 2
	s_barrier
	s_add_i32 s53, s53, 2
	s_add_u32 s14, s14, 0x100
	s_addc_u32 s15, s15, 0
	s_add_u32 s51, s51, 0x100
	s_addc_u32 s52, s52, 0
	s_cmp_gt_u32 s53, 13
	s_cbranch_scc0 .LBB0_271
	s_and_b64 vcc, exec, s[12:13]
	s_cbranch_vccz .LBB0_274
	s_barrier

.LBB0_361:
	s_add_u32 s34, s30, 0xfffc0080
	s_addc_u32 s35, s31, -1
	s_add_i32 s62, 0, 0x10000
	s_cmp_eq_u32 s61, 12
	s_cselect_b32 s37, s25, s35
	s_cselect_b32 s36, s57, s34
	v_add_u32_e32 v96, s62, v151
	s_cselect_b32 s35, s15, s60
	s_cselect_b32 s34, s58, s59
	s_add_i32 s64, 0, 0x14000
	ds_read_b128 v[164:167], v96
	ds_read_b128 v[168:171], v96 offset:1024
	ds_read_b128 v[186:189], v96 offset:2048
	ds_read_b128 v[190:193], v96 offset:3072
	v_add_u32_e32 v96, s64, v151
	ds_read_b128 v[194:197], v96
	ds_read_b128 v[198:201], v96 offset:1024
	ds_read_b128 v[202:205], v96 offset:2048
	ds_read_b128 v[206:209], v96 offset:3072
	v_lshl_add_u64 v[154:155], s[30:31], 0, v[146:147]
	s_add_i32 m0, s43, 0xc000
	ds_read_b128 v[210:213], v162
	ds_read_b128 v[214:217], v162 offset:1024
	ds_read_b128 v[218:221], v162 offset:2048
	ds_read_b128 v[222:225], v162 offset:3072
	ds_read_b128 v[226:229], v162 offset:4096
	ds_read_b128 v[230:233], v162 offset:5120
	ds_read_b128 v[242:245], v162 offset:6144
	ds_read_b128 v[246:249], v162 offset:7168
	global_load_lds_dwordx4 v[154:155], off
	s_add_i32 m0, s43, 0xe000
	v_lshl_add_u64 v[154:155], s[30:31], 0, v[148:149]
	global_load_lds_dwordx4 v[154:155], off
	s_setprio 1
	s_waitcnt vmcnt(8) lgkmcnt(0)
	s_barrier
	v_mfma_f32_16x16x32_bf16 v[126:129], v[164:167], v[210:213], v[126:129]
	v_mfma_f32_16x16x32_bf16 v[122:125], v[186:189], v[210:213], v[122:125]
	v_mfma_f32_16x16x32_bf16 v[118:121], v[164:167], v[218:221], v[118:121]
	v_mfma_f32_16x16x32_bf16 v[114:117], v[186:189], v[218:221], v[114:117]
	v_mfma_f32_16x16x32_bf16 v[110:113], v[164:167], v[226:229], v[110:113]
	v_mfma_f32_16x16x32_bf16 v[106:109], v[186:189], v[226:229], v[106:109]
	v_mfma_f32_16x16x32_bf16 v[102:105], v[164:167], v[242:245], v[102:105]
	v_mfma_f32_16x16x32_bf16 v[98:101], v[186:189], v[242:245], v[98:101]
	v_mfma_f32_16x16x32_bf16 v[126:129], v[168:171], v[214:217], v[126:129]
	v_mfma_f32_16x16x32_bf16 v[122:125], v[190:193], v[214:217], v[122:125]
	v_mfma_f32_16x16x32_bf16 v[118:121], v[168:171], v[222:225], v[118:121]
	v_mfma_f32_16x16x32_bf16 v[114:117], v[190:193], v[222:225], v[114:117]
	v_mfma_f32_16x16x32_bf16 v[110:113], v[168:171], v[230:233], v[110:113]
	v_mfma_f32_16x16x32_bf16 v[106:109], v[190:193], v[230:233], v[106:109]
	v_mfma_f32_16x16x32_bf16 v[102:105], v[168:171], v[246:249], v[102:105]
	v_mfma_f32_16x16x32_bf16 v[98:101], v[190:193], v[246:249], v[98:101]
	s_setprio 0
	s_setprio 1
	v_mfma_f32_16x16x32_bf16 v[76:79], v[194:197], v[210:213], v[76:79]
	v_mfma_f32_16x16x32_bf16 v[64:67], v[202:205], v[210:213], v[64:67]
	v_mfma_f32_16x16x32_bf16 v[60:63], v[194:197], v[218:221], v[60:63]
	v_mfma_f32_16x16x32_bf16 v[52:55], v[202:205], v[218:221], v[52:55]
	v_mfma_f32_16x16x32_bf16 v[44:47], v[194:197], v[226:229], v[44:47]
	v_mfma_f32_16x16x32_bf16 v[40:43], v[202:205], v[226:229], v[40:43]
	v_mfma_f32_16x16x32_bf16 v[36:39], v[194:197], v[242:245], v[36:39]
	v_mfma_f32_16x16x32_bf16 v[32:35], v[202:205], v[242:245], v[32:35]
	v_mfma_f32_16x16x32_bf16 v[76:79], v[198:201], v[214:217], v[76:79]
	v_mfma_f32_16x16x32_bf16 v[64:67], v[206:209], v[214:217], v[64:67]
	v_mfma_f32_16x16x32_bf16 v[60:63], v[198:201], v[222:225], v[60:63]
	v_mfma_f32_16x16x32_bf16 v[52:55], v[206:209], v[222:225], v[52:55]
	v_mfma_f32_16x16x32_bf16 v[44:47], v[198:201], v[230:233], v[44:47]
	v_mfma_f32_16x16x32_bf16 v[40:43], v[206:209], v[230:233], v[40:43]
	v_mfma_f32_16x16x32_bf16 v[36:39], v[198:201], v[246:249], v[36:39]
	v_mfma_f32_16x16x32_bf16 v[32:35], v[206:209], v[246:249], v[32:35]
	s_setprio 2
	s_barrier
	s_add_i32 s62, s62, s40
	v_lshl_add_u64 v[154:155], s[34:35], 0, v[134:135]
	s_mov_b32 m0, s62
	ds_read_b128 v[210:213], v162 offset:16384
	ds_read_b128 v[214:217], v162 offset:17408
	ds_read_b128 v[218:221], v162 offset:18432
	ds_read_b128 v[222:225], v162 offset:19456
	ds_read_b128 v[226:229], v162 offset:20480
	ds_read_b128 v[230:233], v162 offset:21504
	ds_read_b128 v[242:245], v162 offset:22528
	ds_read_b128 v[246:249], v162 offset:23552
	global_load_lds_dwordx4 v[154:155], off
	s_add_i32 m0, s62, 0x2000
	s_add_u32 s62, s34, 0x40000
	v_lshl_add_u64 v[156:157], s[34:35], 0, v[130:131]
	s_addc_u32 s63, s35, 0
	s_add_i32 s64, s64, s40
	global_load_lds_dwordx4 v[156:157], off
	v_lshl_add_u64 v[158:159], s[62:63], 0, v[134:135]
	s_mov_b32 m0, s64
	v_lshl_add_u64 v[172:173], s[36:37], 0, v[132:133]
	global_load_lds_dwordx4 v[158:159], off
	s_add_i32 m0, s64, 0x2000
	v_lshl_add_u64 v[158:159], s[62:63], 0, v[130:131]
	global_load_lds_dwordx4 v[158:159], off
	s_mov_b32 m0, s43
	v_lshl_add_u64 v[158:159], s[36:37], 0, v[136:137]
	global_load_lds_dwordx4 v[158:159], off
	s_mov_b32 m0, s44
	s_nop 0
	global_load_lds_dwordx4 v[172:173], off
	s_setprio 1
	s_waitcnt vmcnt(8) lgkmcnt(0)
	s_barrier
	v_mfma_f32_16x16x32_bf16 v[92:95], v[164:167], v[210:213], v[92:95]
	v_mfma_f32_16x16x32_bf16 v[88:91], v[186:189], v[210:213], v[88:91]
	v_mfma_f32_16x16x32_bf16 v[84:87], v[164:167], v[218:221], v[84:87]
	v_mfma_f32_16x16x32_bf16 v[80:83], v[186:189], v[218:221], v[80:83]
	v_mfma_f32_16x16x32_bf16 v[72:75], v[164:167], v[226:229], v[72:75]
	v_mfma_f32_16x16x32_bf16 v[68:71], v[186:189], v[226:229], v[68:71]
	v_mfma_f32_16x16x32_bf16 v[56:59], v[164:167], v[242:245], v[56:59]
	v_mfma_f32_16x16x32_bf16 v[48:51], v[186:189], v[242:245], v[48:51]
	v_mfma_f32_16x16x32_bf16 v[92:95], v[168:171], v[214:217], v[92:95]
	v_mfma_f32_16x16x32_bf16 v[88:91], v[190:193], v[214:217], v[88:91]
	v_mfma_f32_16x16x32_bf16 v[84:87], v[168:171], v[222:225], v[84:87]
	v_mfma_f32_16x16x32_bf16 v[80:83], v[190:193], v[222:225], v[80:83]
	v_mfma_f32_16x16x32_bf16 v[72:75], v[168:171], v[230:233], v[72:75]
	v_mfma_f32_16x16x32_bf16 v[68:71], v[190:193], v[230:233], v[68:71]
	v_mfma_f32_16x16x32_bf16 v[56:59], v[168:171], v[246:249], v[56:59]
	v_mfma_f32_16x16x32_bf16 v[48:51], v[190:193], v[246:249], v[48:51]
	s_setprio 0
	s_setprio 1
	v_mfma_f32_16x16x32_bf16 v[28:31], v[194:197], v[210:213], v[28:31]
	v_mfma_f32_16x16x32_bf16 v[24:27], v[202:205], v[210:213], v[24:27]
	v_mfma_f32_16x16x32_bf16 v[20:23], v[194:197], v[218:221], v[20:23]
	v_mfma_f32_16x16x32_bf16 v[16:19], v[202:205], v[218:221], v[16:19]
	v_mfma_f32_16x16x32_bf16 v[12:15], v[194:197], v[226:229], v[12:15]
	v_mfma_f32_16x16x32_bf16 v[8:11], v[202:205], v[226:229], v[8:11]
	v_mfma_f32_16x16x32_bf16 v[4:7], v[194:197], v[242:245], v[4:7]
	v_mfma_f32_16x16x32_bf16 v[0:3], v[202:205], v[242:245], v[0:3]
	v_mfma_f32_16x16x32_bf16 v[28:31], v[198:201], v[214:217], v[28:31]
	v_mfma_f32_16x16x32_bf16 v[24:27], v[206:209], v[214:217], v[24:27]
	v_mfma_f32_16x16x32_bf16 v[20:23], v[198:201], v[222:225], v[20:23]
	v_mfma_f32_16x16x32_bf16 v[16:19], v[206:209], v[222:225], v[16:19]
	v_mfma_f32_16x16x32_bf16 v[12:15], v[198:201], v[230:233], v[12:15]
	v_mfma_f32_16x16x32_bf16 v[8:11], v[206:209], v[230:233], v[8:11]
	v_mfma_f32_16x16x32_bf16 v[4:7], v[198:201], v[246:249], v[4:7]
	v_mfma_f32_16x16x32_bf16 v[0:3], v[206:209], v[246:249], v[0:3]
	s_setprio 2
	s_barrier
	s_add_i32 s62, 0, 0x18000
	v_add_u32_e32 v96, s62, v151
	s_add_i32 s63, 0, 0x1c000
	ds_read_b128 v[164:167], v96
	ds_read_b128 v[168:171], v96 offset:1024
	ds_read_b128 v[186:189], v96 offset:2048
	ds_read_b128 v[190:193], v96 offset:3072
	v_add_u32_e32 v96, s63, v151
	ds_read_b128 v[194:197], v96
	ds_read_b128 v[198:201], v96 offset:1024
	ds_read_b128 v[202:205], v96 offset:2048
	ds_read_b128 v[206:209], v96 offset:3072
	s_add_u32 s36, s36, 0x40000
	s_addc_u32 s37, s37, 0
	s_mov_b32 m0, s45
	v_lshl_add_u64 v[182:183], s[36:37], 0, v[136:137]
	ds_read_b128 v[210:213], v162 offset:32768
	ds_read_b128 v[214:217], v162 offset:33792
	ds_read_b128 v[218:221], v162 offset:34816
	ds_read_b128 v[222:225], v162 offset:35840
	ds_read_b128 v[226:229], v162 offset:36864
	ds_read_b128 v[230:233], v162 offset:37888
	ds_read_b128 v[242:245], v162 offset:38912
	ds_read_b128 v[246:249], v162 offset:39936
	global_load_lds_dwordx4 v[182:183], off
	s_mov_b32 m0, s46
	v_lshl_add_u64 v[182:183], s[36:37], 0, v[132:133]
	global_load_lds_dwordx4 v[182:183], off
	s_setprio 1
	s_waitcnt vmcnt(8) lgkmcnt(0)
	s_barrier
	v_mfma_f32_16x16x32_bf16 v[126:129], v[164:167], v[210:213], v[126:129]
	v_mfma_f32_16x16x32_bf16 v[122:125], v[186:189], v[210:213], v[122:125]
	v_mfma_f32_16x16x32_bf16 v[118:121], v[164:167], v[218:221], v[118:121]
	v_mfma_f32_16x16x32_bf16 v[114:117], v[186:189], v[218:221], v[114:117]
	v_mfma_f32_16x16x32_bf16 v[110:113], v[164:167], v[226:229], v[110:113]
	v_mfma_f32_16x16x32_bf16 v[106:109], v[186:189], v[226:229], v[106:109]
	v_mfma_f32_16x16x32_bf16 v[102:105], v[164:167], v[242:245], v[102:105]
	v_mfma_f32_16x16x32_bf16 v[98:101], v[186:189], v[242:245], v[98:101]
	v_mfma_f32_16x16x32_bf16 v[126:129], v[168:171], v[214:217], v[126:129]
	v_mfma_f32_16x16x32_bf16 v[122:125], v[190:193], v[214:217], v[122:125]
	v_mfma_f32_16x16x32_bf16 v[118:121], v[168:171], v[222:225], v[118:121]
	v_mfma_f32_16x16x32_bf16 v[114:117], v[190:193], v[222:225], v[114:117]
	v_mfma_f32_16x16x32_bf16 v[110:113], v[168:171], v[230:233], v[110:113]
	v_mfma_f32_16x16x32_bf16 v[106:109], v[190:193], v[230:233], v[106:109]
	v_mfma_f32_16x16x32_bf16 v[102:105], v[168:171], v[246:249], v[102:105]
	v_mfma_f32_16x16x32_bf16 v[98:101], v[190:193], v[246:249], v[98:101]
	s_setprio 0
	s_setprio 1
	v_mfma_f32_16x16x32_bf16 v[76:79], v[194:197], v[210:213], v[76:79]
	v_mfma_f32_16x16x32_bf16 v[64:67], v[202:205], v[210:213], v[64:67]
	v_mfma_f32_16x16x32_bf16 v[60:63], v[194:197], v[218:221], v[60:63]
	v_mfma_f32_16x16x32_bf16 v[52:55], v[202:205], v[218:221], v[52:55]
	v_mfma_f32_16x16x32_bf16 v[44:47], v[194:197], v[226:229], v[44:47]
	v_mfma_f32_16x16x32_bf16 v[40:43], v[202:205], v[226:229], v[40:43]
	v_mfma_f32_16x16x32_bf16 v[36:39], v[194:197], v[242:245], v[36:39]
	v_mfma_f32_16x16x32_bf16 v[32:35], v[202:205], v[242:245], v[32:35]
	v_mfma_f32_16x16x32_bf16 v[76:79], v[198:201], v[214:217], v[76:79]
	v_mfma_f32_16x16x32_bf16 v[64:67], v[206:209], v[214:217], v[64:67]
	v_mfma_f32_16x16x32_bf16 v[60:63], v[198:201], v[222:225], v[60:63]
	v_mfma_f32_16x16x32_bf16 v[52:55], v[206:209], v[222:225], v[52:55]
	v_mfma_f32_16x16x32_bf16 v[44:47], v[198:201], v[230:233], v[44:47]
	v_mfma_f32_16x16x32_bf16 v[40:43], v[206:209], v[230:233], v[40:43]
	v_mfma_f32_16x16x32_bf16 v[36:39], v[198:201], v[246:249], v[36:39]
	v_mfma_f32_16x16x32_bf16 v[32:35], v[206:209], v[246:249], v[32:35]
	s_setprio 2
	s_barrier
	s_add_i32 s36, s62, s40
	v_lshl_add_u64 v[154:155], v[154:155], 0, s[16:17]
	s_mov_b32 m0, s36
	ds_read_b128 v[210:213], v162 offset:49152
	ds_read_b128 v[214:217], v162 offset:50176
	ds_read_b128 v[218:221], v162 offset:51200
	ds_read_b128 v[222:225], v162 offset:52224
	ds_read_b128 v[226:229], v162 offset:53248
	ds_read_b128 v[230:233], v162 offset:54272
	ds_read_b128 v[242:245], v162 offset:55296
	ds_read_b128 v[246:249], v162 offset:56320
	global_load_lds_dwordx4 v[154:155], off
	s_add_i32 m0, s36, 0x2000
	s_add_u32 s34, s34, 0x40080
	v_lshl_add_u64 v[154:155], v[156:157], 0, s[16:17]
	s_addc_u32 s35, s35, 0
	s_add_i32 s36, s63, s40
	global_load_lds_dwordx4 v[154:155], off
	s_mov_b32 m0, s36
	v_lshl_add_u64 v[154:155], s[34:35], 0, v[134:135]
	global_load_lds_dwordx4 v[154:155], off
	s_add_i32 m0, s36, 0x2000
	v_lshl_add_u64 v[154:155], s[34:35], 0, v[130:131]
	global_load_lds_dwordx4 v[154:155], off
	s_mov_b32 m0, s50
	v_lshl_add_u64 v[154:155], v[158:159], 0, s[16:17]
	global_load_lds_dwordx4 v[154:155], off
	s_mov_b32 m0, s51
	v_lshl_add_u64 v[154:155], v[172:173], 0, s[16:17]
	global_load_lds_dwordx4 v[154:155], off
	s_setprio 1
	s_waitcnt vmcnt(8) lgkmcnt(0)
	s_barrier
	v_mfma_f32_16x16x32_bf16 v[92:95], v[164:167], v[210:213], v[92:95]
	v_mfma_f32_16x16x32_bf16 v[88:91], v[186:189], v[210:213], v[88:91]
	v_mfma_f32_16x16x32_bf16 v[84:87], v[164:167], v[218:221], v[84:87]
	v_mfma_f32_16x16x32_bf16 v[80:83], v[186:189], v[218:221], v[80:83]
	v_mfma_f32_16x16x32_bf16 v[72:75], v[164:167], v[226:229], v[72:75]
	v_mfma_f32_16x16x32_bf16 v[68:71], v[186:189], v[226:229], v[68:71]
	v_mfma_f32_16x16x32_bf16 v[56:59], v[164:167], v[242:245], v[56:59]
	v_mfma_f32_16x16x32_bf16 v[48:51], v[186:189], v[242:245], v[48:51]
	v_mfma_f32_16x16x32_bf16 v[92:95], v[168:171], v[214:217], v[92:95]
	v_mfma_f32_16x16x32_bf16 v[88:91], v[190:193], v[214:217], v[88:91]
	v_mfma_f32_16x16x32_bf16 v[84:87], v[168:171], v[222:225], v[84:87]
	v_mfma_f32_16x16x32_bf16 v[80:83], v[190:193], v[222:225], v[80:83]
	v_mfma_f32_16x16x32_bf16 v[72:75], v[168:171], v[230:233], v[72:75]
	v_mfma_f32_16x16x32_bf16 v[68:71], v[190:193], v[230:233], v[68:71]
	v_mfma_f32_16x16x32_bf16 v[56:59], v[168:171], v[246:249], v[56:59]
	v_mfma_f32_16x16x32_bf16 v[48:51], v[190:193], v[246:249], v[48:51]
	s_setprio 0
	s_setprio 1
	v_mfma_f32_16x16x32_bf16 v[28:31], v[194:197], v[210:213], v[28:31]
	v_mfma_f32_16x16x32_bf16 v[24:27], v[202:205], v[210:213], v[24:27]
	v_mfma_f32_16x16x32_bf16 v[20:23], v[194:197], v[218:221], v[20:23]
	v_mfma_f32_16x16x32_bf16 v[16:19], v[202:205], v[218:221], v[16:19]
	v_mfma_f32_16x16x32_bf16 v[12:15], v[194:197], v[226:229], v[12:15]
	v_mfma_f32_16x16x32_bf16 v[8:11], v[202:205], v[226:229], v[8:11]
	v_mfma_f32_16x16x32_bf16 v[4:7], v[194:197], v[242:245], v[4:7]
	v_mfma_f32_16x16x32_bf16 v[0:3], v[202:205], v[242:245], v[0:3]
	v_mfma_f32_16x16x32_bf16 v[28:31], v[198:201], v[214:217], v[28:31]
	v_mfma_f32_16x16x32_bf16 v[24:27], v[206:209], v[214:217], v[24:27]
	v_mfma_f32_16x16x32_bf16 v[20:23], v[198:201], v[222:225], v[20:23]
	v_mfma_f32_16x16x32_bf16 v[16:19], v[206:209], v[222:225], v[16:19]
	v_mfma_f32_16x16x32_bf16 v[12:15], v[198:201], v[230:233], v[12:15]
	v_mfma_f32_16x16x32_bf16 v[8:11], v[206:209], v[230:233], v[8:11]
	v_mfma_f32_16x16x32_bf16 v[4:7], v[198:201], v[246:249], v[4:7]
	v_mfma_f32_16x16x32_bf16 v[0:3], v[206:209], v[246:249], v[0:3]
	s_setprio 2
	s_barrier
	s_add_i32 s61, s61, 2
	s_add_u32 s30, s30, 0x100
	s_addc_u32 s31, s31, 0
	s_add_u32 s59, s59, 0x100
	s_addc_u32 s60, s60, 0
	s_cmp_gt_u32 s61, 13
	s_cbranch_scc0 .LBB0_361
	s_and_b64 vcc, exec, s[20:21]
	s_cbranch_vccz .LBB0_364
	s_barrier

.LBB0_393:
	s_add_u32 s26, s14, 0xfffc0080
	s_addc_u32 s27, s15, -1
	s_add_i32 s57, 0, 0x10000
	s_cmp_eq_u32 s56, 12
	s_cselect_b32 s29, s19, s27
	s_cselect_b32 s28, s52, s26
	v_add_u32_e32 v151, s57, v141
	s_cselect_b32 s27, s5, s55
	s_cselect_b32 s26, s53, s54
	s_add_i32 s60, 0, 0x14000
	ds_read_b128 v[162:165], v151
	ds_read_b128 v[166:169], v151 offset:1024
	ds_read_b128 v[170:173], v151 offset:2048
	ds_read_b128 v[186:189], v151 offset:3072
	v_add_u32_e32 v151, s60, v141
	ds_read_b128 v[190:193], v151
	ds_read_b128 v[194:197], v151 offset:1024
	ds_read_b128 v[198:201], v151 offset:2048
	ds_read_b128 v[202:205], v151 offset:3072
	v_lshl_add_u64 v[152:153], s[14:15], 0, v[146:147]
	s_add_i32 m0, s39, 0xc000
	ds_read_b128 v[206:209], v150
	ds_read_b128 v[210:213], v150 offset:1024
	ds_read_b128 v[214:217], v150 offset:2048
	ds_read_b128 v[218:221], v150 offset:3072
	ds_read_b128 v[222:225], v150 offset:4096
	ds_read_b128 v[226:229], v150 offset:5120
	ds_read_b128 v[230:233], v150 offset:6144
	ds_read_b128 v[242:245], v150 offset:7168
	global_load_lds_dwordx4 v[152:153], off
	s_add_i32 m0, s39, 0xe000
	v_lshl_add_u64 v[152:153], s[14:15], 0, v[148:149]
	global_load_lds_dwordx4 v[152:153], off
	s_setprio 1
	s_waitcnt vmcnt(8) lgkmcnt(0)
	s_barrier
	v_mfma_f32_16x16x32_bf16 v[126:129], v[162:165], v[206:209], v[126:129]
	v_mfma_f32_16x16x32_bf16 v[122:125], v[170:173], v[206:209], v[122:125]
	v_mfma_f32_16x16x32_bf16 v[118:121], v[162:165], v[214:217], v[118:121]
	v_mfma_f32_16x16x32_bf16 v[114:117], v[170:173], v[214:217], v[114:117]
	v_mfma_f32_16x16x32_bf16 v[110:113], v[162:165], v[222:225], v[110:113]
	v_mfma_f32_16x16x32_bf16 v[106:109], v[170:173], v[222:225], v[106:109]
	v_mfma_f32_16x16x32_bf16 v[102:105], v[162:165], v[230:233], v[102:105]
	v_mfma_f32_16x16x32_bf16 v[98:101], v[170:173], v[230:233], v[98:101]
	v_mfma_f32_16x16x32_bf16 v[126:129], v[166:169], v[210:213], v[126:129]
	v_mfma_f32_16x16x32_bf16 v[122:125], v[186:189], v[210:213], v[122:125]
	v_mfma_f32_16x16x32_bf16 v[118:121], v[166:169], v[218:221], v[118:121]
	v_mfma_f32_16x16x32_bf16 v[114:117], v[186:189], v[218:221], v[114:117]
	v_mfma_f32_16x16x32_bf16 v[110:113], v[166:169], v[226:229], v[110:113]
	v_mfma_f32_16x16x32_bf16 v[106:109], v[186:189], v[226:229], v[106:109]
	v_mfma_f32_16x16x32_bf16 v[102:105], v[166:169], v[242:245], v[102:105]
	v_mfma_f32_16x16x32_bf16 v[98:101], v[186:189], v[242:245], v[98:101]
	s_setprio 0
	s_setprio 1
	v_mfma_f32_16x16x32_bf16 v[68:71], v[190:193], v[206:209], v[68:71]
	v_mfma_f32_16x16x32_bf16 v[64:67], v[198:201], v[206:209], v[64:67]
	v_mfma_f32_16x16x32_bf16 v[52:55], v[190:193], v[214:217], v[52:55]
	v_mfma_f32_16x16x32_bf16 v[48:51], v[198:201], v[214:217], v[48:51]
	v_mfma_f32_16x16x32_bf16 v[44:47], v[190:193], v[222:225], v[44:47]
	v_mfma_f32_16x16x32_bf16 v[40:43], v[198:201], v[222:225], v[40:43]
	v_mfma_f32_16x16x32_bf16 v[36:39], v[190:193], v[230:233], v[36:39]
	v_mfma_f32_16x16x32_bf16 v[32:35], v[198:201], v[230:233], v[32:35]
	v_mfma_f32_16x16x32_bf16 v[68:71], v[194:197], v[210:213], v[68:71]
	v_mfma_f32_16x16x32_bf16 v[64:67], v[202:205], v[210:213], v[64:67]
	v_mfma_f32_16x16x32_bf16 v[52:55], v[194:197], v[218:221], v[52:55]
	v_mfma_f32_16x16x32_bf16 v[48:51], v[202:205], v[218:221], v[48:51]
	v_mfma_f32_16x16x32_bf16 v[44:47], v[194:197], v[226:229], v[44:47]
	v_mfma_f32_16x16x32_bf16 v[40:43], v[202:205], v[226:229], v[40:43]
	v_mfma_f32_16x16x32_bf16 v[36:39], v[194:197], v[242:245], v[36:39]
	v_mfma_f32_16x16x32_bf16 v[32:35], v[202:205], v[242:245], v[32:35]
	s_setprio 2
	s_barrier
	s_add_i32 s57, s57, s36
	v_lshl_add_u64 v[152:153], s[26:27], 0, v[96:97]
	s_mov_b32 m0, s57
	ds_read_b128 v[206:209], v150 offset:16384
	ds_read_b128 v[210:213], v150 offset:17408
	ds_read_b128 v[214:217], v150 offset:18432
	ds_read_b128 v[218:221], v150 offset:19456
	ds_read_b128 v[222:225], v150 offset:20480
	ds_read_b128 v[226:229], v150 offset:21504
	ds_read_b128 v[230:233], v150 offset:22528
	ds_read_b128 v[242:245], v150 offset:23552
	global_load_lds_dwordx4 v[152:153], off
	s_add_i32 m0, s57, 0x2000
	s_add_u32 s58, s26, 0x40000
	v_lshl_add_u64 v[154:155], s[26:27], 0, v[130:131]
	s_addc_u32 s59, s27, 0
	s_add_i32 s57, s60, s36
	global_load_lds_dwordx4 v[154:155], off
	v_lshl_add_u64 v[156:157], s[58:59], 0, v[96:97]
	s_mov_b32 m0, s57
	v_lshl_add_u64 v[158:159], s[28:29], 0, v[132:133]
	global_load_lds_dwordx4 v[156:157], off
	s_add_i32 m0, s57, 0x2000
	v_lshl_add_u64 v[156:157], s[58:59], 0, v[130:131]
	global_load_lds_dwordx4 v[156:157], off
	s_mov_b32 m0, s39
	v_lshl_add_u64 v[156:157], s[28:29], 0, v[134:135]
	global_load_lds_dwordx4 v[156:157], off
	s_mov_b32 m0, s40
	s_nop 0
	global_load_lds_dwordx4 v[158:159], off
	s_setprio 1
	s_waitcnt vmcnt(8) lgkmcnt(0)
	s_barrier
	v_mfma_f32_16x16x32_bf16 v[92:95], v[162:165], v[206:209], v[92:95]
	v_mfma_f32_16x16x32_bf16 v[88:91], v[170:173], v[206:209], v[88:91]
	v_mfma_f32_16x16x32_bf16 v[84:87], v[162:165], v[214:217], v[84:87]
	v_mfma_f32_16x16x32_bf16 v[80:83], v[170:173], v[214:217], v[80:83]
	v_mfma_f32_16x16x32_bf16 v[76:79], v[162:165], v[222:225], v[76:79]
	v_mfma_f32_16x16x32_bf16 v[72:75], v[170:173], v[222:225], v[72:75]
	v_mfma_f32_16x16x32_bf16 v[60:63], v[162:165], v[230:233], v[60:63]
	v_mfma_f32_16x16x32_bf16 v[56:59], v[170:173], v[230:233], v[56:59]
	v_mfma_f32_16x16x32_bf16 v[92:95], v[166:169], v[210:213], v[92:95]
	v_mfma_f32_16x16x32_bf16 v[88:91], v[186:189], v[210:213], v[88:91]
	v_mfma_f32_16x16x32_bf16 v[84:87], v[166:169], v[218:221], v[84:87]
	v_mfma_f32_16x16x32_bf16 v[80:83], v[186:189], v[218:221], v[80:83]
	v_mfma_f32_16x16x32_bf16 v[76:79], v[166:169], v[226:229], v[76:79]
	v_mfma_f32_16x16x32_bf16 v[72:75], v[186:189], v[226:229], v[72:75]
	v_mfma_f32_16x16x32_bf16 v[60:63], v[166:169], v[242:245], v[60:63]
	v_mfma_f32_16x16x32_bf16 v[56:59], v[186:189], v[242:245], v[56:59]
	s_setprio 0
	s_setprio 1
	v_mfma_f32_16x16x32_bf16 v[28:31], v[190:193], v[206:209], v[28:31]
	v_mfma_f32_16x16x32_bf16 v[24:27], v[198:201], v[206:209], v[24:27]
	v_mfma_f32_16x16x32_bf16 v[20:23], v[190:193], v[214:217], v[20:23]
	v_mfma_f32_16x16x32_bf16 v[16:19], v[198:201], v[214:217], v[16:19]
	v_mfma_f32_16x16x32_bf16 v[12:15], v[190:193], v[222:225], v[12:15]
	v_mfma_f32_16x16x32_bf16 v[8:11], v[198:201], v[222:225], v[8:11]
	v_mfma_f32_16x16x32_bf16 v[4:7], v[190:193], v[230:233], v[4:7]
	v_mfma_f32_16x16x32_bf16 v[0:3], v[198:201], v[230:233], v[0:3]
	v_mfma_f32_16x16x32_bf16 v[28:31], v[194:197], v[210:213], v[28:31]
	v_mfma_f32_16x16x32_bf16 v[24:27], v[202:205], v[210:213], v[24:27]
	v_mfma_f32_16x16x32_bf16 v[20:23], v[194:197], v[218:221], v[20:23]
	v_mfma_f32_16x16x32_bf16 v[16:19], v[202:205], v[218:221], v[16:19]
	v_mfma_f32_16x16x32_bf16 v[12:15], v[194:197], v[226:229], v[12:15]
	v_mfma_f32_16x16x32_bf16 v[8:11], v[202:205], v[226:229], v[8:11]
	v_mfma_f32_16x16x32_bf16 v[4:7], v[194:197], v[242:245], v[4:7]
	v_mfma_f32_16x16x32_bf16 v[0:3], v[202:205], v[242:245], v[0:3]
	s_setprio 2
	s_barrier
	s_add_i32 s57, 0, 0x18000
	v_add_u32_e32 v151, s57, v141
	s_add_i32 s58, 0, 0x1c000
	ds_read_b128 v[162:165], v151
	ds_read_b128 v[166:169], v151 offset:1024
	ds_read_b128 v[170:173], v151 offset:2048
	ds_read_b128 v[186:189], v151 offset:3072
	v_add_u32_e32 v151, s58, v141
	ds_read_b128 v[190:193], v151
	ds_read_b128 v[194:197], v151 offset:1024
	ds_read_b128 v[198:201], v151 offset:2048
	ds_read_b128 v[202:205], v151 offset:3072
	s_add_u32 s28, s28, 0x40000
	s_addc_u32 s29, s29, 0
	s_mov_b32 m0, s41
	v_lshl_add_u64 v[182:183], s[28:29], 0, v[134:135]
	ds_read_b128 v[206:209], v150 offset:32768
	ds_read_b128 v[210:213], v150 offset:33792
	ds_read_b128 v[214:217], v150 offset:34816
	ds_read_b128 v[218:221], v150 offset:35840
	ds_read_b128 v[222:225], v150 offset:36864
	ds_read_b128 v[226:229], v150 offset:37888
	ds_read_b128 v[230:233], v150 offset:38912
	ds_read_b128 v[242:245], v150 offset:39936
	global_load_lds_dwordx4 v[182:183], off
	s_mov_b32 m0, s42
	v_lshl_add_u64 v[182:183], s[28:29], 0, v[132:133]
	global_load_lds_dwordx4 v[182:183], off
	s_setprio 1
	s_waitcnt vmcnt(8) lgkmcnt(0)
	s_barrier
	v_mfma_f32_16x16x32_bf16 v[126:129], v[162:165], v[206:209], v[126:129]
	v_mfma_f32_16x16x32_bf16 v[122:125], v[170:173], v[206:209], v[122:125]
	v_mfma_f32_16x16x32_bf16 v[118:121], v[162:165], v[214:217], v[118:121]
	v_mfma_f32_16x16x32_bf16 v[114:117], v[170:173], v[214:217], v[114:117]
	v_mfma_f32_16x16x32_bf16 v[110:113], v[162:165], v[222:225], v[110:113]
	v_mfma_f32_16x16x32_bf16 v[106:109], v[170:173], v[222:225], v[106:109]
	v_mfma_f32_16x16x32_bf16 v[102:105], v[162:165], v[230:233], v[102:105]
	v_mfma_f32_16x16x32_bf16 v[98:101], v[170:173], v[230:233], v[98:101]
	v_mfma_f32_16x16x32_bf16 v[126:129], v[166:169], v[210:213], v[126:129]
	v_mfma_f32_16x16x32_bf16 v[122:125], v[186:189], v[210:213], v[122:125]
	v_mfma_f32_16x16x32_bf16 v[118:121], v[166:169], v[218:221], v[118:121]
	v_mfma_f32_16x16x32_bf16 v[114:117], v[186:189], v[218:221], v[114:117]
	v_mfma_f32_16x16x32_bf16 v[110:113], v[166:169], v[226:229], v[110:113]
	v_mfma_f32_16x16x32_bf16 v[106:109], v[186:189], v[226:229], v[106:109]
	v_mfma_f32_16x16x32_bf16 v[102:105], v[166:169], v[242:245], v[102:105]
	v_mfma_f32_16x16x32_bf16 v[98:101], v[186:189], v[242:245], v[98:101]
	s_setprio 0
	s_setprio 1
	v_mfma_f32_16x16x32_bf16 v[68:71], v[190:193], v[206:209], v[68:71]
	v_mfma_f32_16x16x32_bf16 v[64:67], v[198:201], v[206:209], v[64:67]
	v_mfma_f32_16x16x32_bf16 v[52:55], v[190:193], v[214:217], v[52:55]
	v_mfma_f32_16x16x32_bf16 v[48:51], v[198:201], v[214:217], v[48:51]
	v_mfma_f32_16x16x32_bf16 v[44:47], v[190:193], v[222:225], v[44:47]
	v_mfma_f32_16x16x32_bf16 v[40:43], v[198:201], v[222:225], v[40:43]
	v_mfma_f32_16x16x32_bf16 v[36:39], v[190:193], v[230:233], v[36:39]
	v_mfma_f32_16x16x32_bf16 v[32:35], v[198:201], v[230:233], v[32:35]
	v_mfma_f32_16x16x32_bf16 v[68:71], v[194:197], v[210:213], v[68:71]
	v_mfma_f32_16x16x32_bf16 v[64:67], v[202:205], v[210:213], v[64:67]
	v_mfma_f32_16x16x32_bf16 v[52:55], v[194:197], v[218:221], v[52:55]
	v_mfma_f32_16x16x32_bf16 v[48:51], v[202:205], v[218:221], v[48:51]
	v_mfma_f32_16x16x32_bf16 v[44:47], v[194:197], v[226:229], v[44:47]
	v_mfma_f32_16x16x32_bf16 v[40:43], v[202:205], v[226:229], v[40:43]
	v_mfma_f32_16x16x32_bf16 v[36:39], v[194:197], v[242:245], v[36:39]
	v_mfma_f32_16x16x32_bf16 v[32:35], v[202:205], v[242:245], v[32:35]
	s_setprio 2
	s_barrier
	s_add_i32 s28, s57, s36
	v_lshl_add_u64 v[152:153], v[152:153], 0, s[16:17]
	s_mov_b32 m0, s28
	ds_read_b128 v[206:209], v150 offset:49152
	ds_read_b128 v[210:213], v150 offset:50176
	ds_read_b128 v[214:217], v150 offset:51200
	ds_read_b128 v[218:221], v150 offset:52224
	ds_read_b128 v[222:225], v150 offset:53248
	ds_read_b128 v[226:229], v150 offset:54272
	ds_read_b128 v[230:233], v150 offset:55296
	ds_read_b128 v[242:245], v150 offset:56320
	global_load_lds_dwordx4 v[152:153], off
	s_add_i32 m0, s28, 0x2000
	s_add_u32 s26, s26, 0x40080
	v_lshl_add_u64 v[152:153], v[154:155], 0, s[16:17]
	s_addc_u32 s27, s27, 0
	s_add_i32 s28, s58, s36
	global_load_lds_dwordx4 v[152:153], off
	s_mov_b32 m0, s28
	v_lshl_add_u64 v[152:153], s[26:27], 0, v[96:97]
	global_load_lds_dwordx4 v[152:153], off
	s_add_i32 m0, s28, 0x2000
	v_lshl_add_u64 v[152:153], s[26:27], 0, v[130:131]
	global_load_lds_dwordx4 v[152:153], off
	s_mov_b32 m0, s45
	v_lshl_add_u64 v[152:153], v[156:157], 0, s[16:17]
	global_load_lds_dwordx4 v[152:153], off
	s_mov_b32 m0, s46
	v_lshl_add_u64 v[152:153], v[158:159], 0, s[16:17]
	global_load_lds_dwordx4 v[152:153], off
	s_setprio 1
	s_waitcnt vmcnt(8) lgkmcnt(0)
	s_barrier
	v_mfma_f32_16x16x32_bf16 v[92:95], v[162:165], v[206:209], v[92:95]
	v_mfma_f32_16x16x32_bf16 v[88:91], v[170:173], v[206:209], v[88:91]
	v_mfma_f32_16x16x32_bf16 v[84:87], v[162:165], v[214:217], v[84:87]
	v_mfma_f32_16x16x32_bf16 v[80:83], v[170:173], v[214:217], v[80:83]
	v_mfma_f32_16x16x32_bf16 v[76:79], v[162:165], v[222:225], v[76:79]
	v_mfma_f32_16x16x32_bf16 v[72:75], v[170:173], v[222:225], v[72:75]
	v_mfma_f32_16x16x32_bf16 v[60:63], v[162:165], v[230:233], v[60:63]
	v_mfma_f32_16x16x32_bf16 v[56:59], v[170:173], v[230:233], v[56:59]
	v_mfma_f32_16x16x32_bf16 v[92:95], v[166:169], v[210:213], v[92:95]
	v_mfma_f32_16x16x32_bf16 v[88:91], v[186:189], v[210:213], v[88:91]
	v_mfma_f32_16x16x32_bf16 v[84:87], v[166:169], v[218:221], v[84:87]
	v_mfma_f32_16x16x32_bf16 v[80:83], v[186:189], v[218:221], v[80:83]
	v_mfma_f32_16x16x32_bf16 v[76:79], v[166:169], v[226:229], v[76:79]
	v_mfma_f32_16x16x32_bf16 v[72:75], v[186:189], v[226:229], v[72:75]
	v_mfma_f32_16x16x32_bf16 v[60:63], v[166:169], v[242:245], v[60:63]
	v_mfma_f32_16x16x32_bf16 v[56:59], v[186:189], v[242:245], v[56:59]
	s_setprio 0
	s_setprio 1
	v_mfma_f32_16x16x32_bf16 v[28:31], v[190:193], v[206:209], v[28:31]
	v_mfma_f32_16x16x32_bf16 v[24:27], v[198:201], v[206:209], v[24:27]
	v_mfma_f32_16x16x32_bf16 v[20:23], v[190:193], v[214:217], v[20:23]
	v_mfma_f32_16x16x32_bf16 v[16:19], v[198:201], v[214:217], v[16:19]
	v_mfma_f32_16x16x32_bf16 v[12:15], v[190:193], v[222:225], v[12:15]
	v_mfma_f32_16x16x32_bf16 v[8:11], v[198:201], v[222:225], v[8:11]
	v_mfma_f32_16x16x32_bf16 v[4:7], v[190:193], v[230:233], v[4:7]
	v_mfma_f32_16x16x32_bf16 v[0:3], v[198:201], v[230:233], v[0:3]
	v_mfma_f32_16x16x32_bf16 v[28:31], v[194:197], v[210:213], v[28:31]
	v_mfma_f32_16x16x32_bf16 v[24:27], v[202:205], v[210:213], v[24:27]
	v_mfma_f32_16x16x32_bf16 v[20:23], v[194:197], v[218:221], v[20:23]
	v_mfma_f32_16x16x32_bf16 v[16:19], v[202:205], v[218:221], v[16:19]
	v_mfma_f32_16x16x32_bf16 v[12:15], v[194:197], v[226:229], v[12:15]
	v_mfma_f32_16x16x32_bf16 v[8:11], v[202:205], v[226:229], v[8:11]
	v_mfma_f32_16x16x32_bf16 v[4:7], v[194:197], v[242:245], v[4:7]
	v_mfma_f32_16x16x32_bf16 v[0:3], v[202:205], v[242:245], v[0:3]
	s_setprio 2
	s_barrier
	s_add_i32 s56, s56, 2
	s_add_u32 s14, s14, 0x100
	s_addc_u32 s15, s15, 0
	s_add_u32 s54, s54, 0x100
	s_addc_u32 s55, s55, 0
	s_cmp_gt_u32 s56, 13
	s_cbranch_scc0 .LBB0_393
	s_and_b64 vcc, exec, s[12:13]
	s_cbranch_vccz .LBB0_396
	s_barrier

.LBB0_427:
	s_add_u32 s14, s4, 0xfffc0080
	s_addc_u32 s15, s5, -1
	s_add_i32 s62, 0, 0x10000
	s_cmp_eq_u32 s61, 12
	s_cselect_b32 s37, s29, s15
	s_cselect_b32 s36, s57, s14
	v_add_u32_e32 v154, s62, v169
	s_cselect_b32 s15, s27, s60
	s_cselect_b32 s14, s58, s59
	s_add_i32 s64, 0, 0x14000
	ds_read_b128 v[142:145], v154
	ds_read_b128 v[146:149], v154 offset:1024
	ds_read_b128 v[150:153], v154 offset:2048
	ds_read_b128 v[162:165], v154 offset:3072
	v_add_u32_e32 v154, s64, v169
	ds_read_b128 v[186:189], v154
	ds_read_b128 v[190:193], v154 offset:1024
	ds_read_b128 v[194:197], v154 offset:2048
	ds_read_b128 v[198:201], v154 offset:3072
	v_lshl_add_u64 v[154:155], s[4:5], 0, v[138:139]
	s_add_i32 m0, s43, 0xc000
	ds_read_b128 v[202:205], v173
	ds_read_b128 v[206:209], v173 offset:1024
	ds_read_b128 v[210:213], v173 offset:2048
	ds_read_b128 v[214:217], v173 offset:3072
	ds_read_b128 v[218:221], v173 offset:4096
	ds_read_b128 v[222:225], v173 offset:5120
	ds_read_b128 v[226:229], v173 offset:6144
	ds_read_b128 v[230:233], v173 offset:7168
	global_load_lds_dwordx4 v[154:155], off
	s_add_i32 m0, s43, 0xe000
	v_lshl_add_u64 v[154:155], s[4:5], 0, v[140:141]
	global_load_lds_dwordx4 v[154:155], off
	s_setprio 1
	s_waitcnt vmcnt(8) lgkmcnt(0)
	s_barrier
	v_mfma_f32_16x16x32_bf16 v[126:129], v[142:145], v[202:205], v[126:129]
	v_mfma_f32_16x16x32_bf16 v[122:125], v[150:153], v[202:205], v[122:125]
	v_mfma_f32_16x16x32_bf16 v[110:113], v[142:145], v[210:213], v[110:113]
	v_mfma_f32_16x16x32_bf16 v[106:109], v[150:153], v[210:213], v[106:109]
	v_mfma_f32_16x16x32_bf16 v[92:95], v[142:145], v[218:221], v[92:95]
	v_mfma_f32_16x16x32_bf16 v[88:91], v[150:153], v[218:221], v[88:91]
	v_mfma_f32_16x16x32_bf16 v[76:79], v[142:145], v[226:229], v[76:79]
	v_mfma_f32_16x16x32_bf16 v[72:75], v[150:153], v[226:229], v[72:75]
	v_mfma_f32_16x16x32_bf16 v[126:129], v[146:149], v[206:209], v[126:129]
	v_mfma_f32_16x16x32_bf16 v[122:125], v[162:165], v[206:209], v[122:125]
	v_mfma_f32_16x16x32_bf16 v[110:113], v[146:149], v[214:217], v[110:113]
	v_mfma_f32_16x16x32_bf16 v[106:109], v[162:165], v[214:217], v[106:109]
	v_mfma_f32_16x16x32_bf16 v[92:95], v[146:149], v[222:225], v[92:95]
	v_mfma_f32_16x16x32_bf16 v[88:91], v[162:165], v[222:225], v[88:91]
	v_mfma_f32_16x16x32_bf16 v[76:79], v[146:149], v[230:233], v[76:79]
	v_mfma_f32_16x16x32_bf16 v[72:75], v[162:165], v[230:233], v[72:75]
	s_setprio 0
	s_setprio 1
	v_mfma_f32_16x16x32_bf16 v[118:121], v[186:189], v[202:205], v[118:121]
	v_mfma_f32_16x16x32_bf16 v[114:117], v[194:197], v[202:205], v[114:117]
	v_mfma_f32_16x16x32_bf16 v[102:105], v[186:189], v[210:213], v[102:105]
	v_mfma_f32_16x16x32_bf16 v[98:101], v[194:197], v[210:213], v[98:101]
	v_mfma_f32_16x16x32_bf16 v[84:87], v[186:189], v[218:221], v[84:87]
	v_mfma_f32_16x16x32_bf16 v[80:83], v[194:197], v[218:221], v[80:83]
	v_mfma_f32_16x16x32_bf16 v[68:71], v[186:189], v[226:229], v[68:71]
	v_mfma_f32_16x16x32_bf16 v[64:67], v[194:197], v[226:229], v[64:67]
	v_mfma_f32_16x16x32_bf16 v[118:121], v[190:193], v[206:209], v[118:121]
	v_mfma_f32_16x16x32_bf16 v[114:117], v[198:201], v[206:209], v[114:117]
	v_mfma_f32_16x16x32_bf16 v[102:105], v[190:193], v[214:217], v[102:105]
	v_mfma_f32_16x16x32_bf16 v[98:101], v[198:201], v[214:217], v[98:101]
	v_mfma_f32_16x16x32_bf16 v[84:87], v[190:193], v[222:225], v[84:87]
	v_mfma_f32_16x16x32_bf16 v[80:83], v[198:201], v[222:225], v[80:83]
	v_mfma_f32_16x16x32_bf16 v[68:71], v[190:193], v[230:233], v[68:71]
	v_mfma_f32_16x16x32_bf16 v[64:67], v[198:201], v[230:233], v[64:67]
	s_setprio 2
	s_barrier
	s_add_i32 s62, s62, s42
	v_lshl_add_u64 v[154:155], s[14:15], 0, v[96:97]
	s_mov_b32 m0, s62
	ds_read_b128 v[202:205], v173 offset:16384
	ds_read_b128 v[206:209], v173 offset:17408
	ds_read_b128 v[210:213], v173 offset:18432
	ds_read_b128 v[214:217], v173 offset:19456
	ds_read_b128 v[218:221], v173 offset:20480
	ds_read_b128 v[222:225], v173 offset:21504
	ds_read_b128 v[226:229], v173 offset:22528
	ds_read_b128 v[230:233], v173 offset:23552
	global_load_lds_dwordx4 v[154:155], off
	s_add_i32 m0, s62, 0x2000
	s_add_u32 s62, s14, 0x40000
	v_lshl_add_u64 v[156:157], s[14:15], 0, v[130:131]
	s_addc_u32 s63, s15, 0
	s_add_i32 s64, s64, s42
	global_load_lds_dwordx4 v[156:157], off
	v_lshl_add_u64 v[158:159], s[62:63], 0, v[96:97]
	s_mov_b32 m0, s64
	v_lshl_add_u64 v[166:167], s[36:37], 0, v[132:133]
	global_load_lds_dwordx4 v[158:159], off
	s_add_i32 m0, s64, 0x2000
	v_lshl_add_u64 v[158:159], s[62:63], 0, v[130:131]
	global_load_lds_dwordx4 v[158:159], off
	s_mov_b32 m0, s43
	v_lshl_add_u64 v[158:159], s[36:37], 0, v[134:135]
	global_load_lds_dwordx4 v[158:159], off
	s_mov_b32 m0, s44
	s_nop 0
	global_load_lds_dwordx4 v[166:167], off
	s_setprio 1
	s_waitcnt vmcnt(8) lgkmcnt(0)
	s_barrier
	v_mfma_f32_16x16x32_bf16 v[60:63], v[142:145], v[202:205], v[60:63]
	v_mfma_f32_16x16x32_bf16 v[56:59], v[150:153], v[202:205], v[56:59]
	v_mfma_f32_16x16x32_bf16 v[44:47], v[142:145], v[210:213], v[44:47]
	v_mfma_f32_16x16x32_bf16 v[40:43], v[150:153], v[210:213], v[40:43]
	v_mfma_f32_16x16x32_bf16 v[28:31], v[142:145], v[218:221], v[28:31]
	v_mfma_f32_16x16x32_bf16 v[24:27], v[150:153], v[218:221], v[24:27]
	v_mfma_f32_16x16x32_bf16 v[12:15], v[142:145], v[226:229], v[12:15]
	v_mfma_f32_16x16x32_bf16 v[8:11], v[150:153], v[226:229], v[8:11]
	v_mfma_f32_16x16x32_bf16 v[60:63], v[146:149], v[206:209], v[60:63]
	v_mfma_f32_16x16x32_bf16 v[56:59], v[162:165], v[206:209], v[56:59]
	v_mfma_f32_16x16x32_bf16 v[44:47], v[146:149], v[214:217], v[44:47]
	v_mfma_f32_16x16x32_bf16 v[40:43], v[162:165], v[214:217], v[40:43]
	v_mfma_f32_16x16x32_bf16 v[28:31], v[146:149], v[222:225], v[28:31]
	v_mfma_f32_16x16x32_bf16 v[24:27], v[162:165], v[222:225], v[24:27]
	v_mfma_f32_16x16x32_bf16 v[12:15], v[146:149], v[230:233], v[12:15]
	v_mfma_f32_16x16x32_bf16 v[8:11], v[162:165], v[230:233], v[8:11]
	s_setprio 0
	s_setprio 1
	v_mfma_f32_16x16x32_bf16 v[52:55], v[186:189], v[202:205], v[52:55]
	v_mfma_f32_16x16x32_bf16 v[48:51], v[194:197], v[202:205], v[48:51]
	v_mfma_f32_16x16x32_bf16 v[36:39], v[186:189], v[210:213], v[36:39]
	v_mfma_f32_16x16x32_bf16 v[32:35], v[194:197], v[210:213], v[32:35]
	v_mfma_f32_16x16x32_bf16 v[20:23], v[186:189], v[218:221], v[20:23]
	v_mfma_f32_16x16x32_bf16 v[16:19], v[194:197], v[218:221], v[16:19]
	v_mfma_f32_16x16x32_bf16 v[4:7], v[186:189], v[226:229], v[4:7]
	v_mfma_f32_16x16x32_bf16 v[0:3], v[194:197], v[226:229], v[0:3]
	v_mfma_f32_16x16x32_bf16 v[52:55], v[190:193], v[206:209], v[52:55]
	v_mfma_f32_16x16x32_bf16 v[48:51], v[198:201], v[206:209], v[48:51]
	v_mfma_f32_16x16x32_bf16 v[36:39], v[190:193], v[214:217], v[36:39]
	v_mfma_f32_16x16x32_bf16 v[32:35], v[198:201], v[214:217], v[32:35]
	v_mfma_f32_16x16x32_bf16 v[20:23], v[190:193], v[222:225], v[20:23]
	v_mfma_f32_16x16x32_bf16 v[16:19], v[198:201], v[222:225], v[16:19]
	v_mfma_f32_16x16x32_bf16 v[4:7], v[190:193], v[230:233], v[4:7]
	v_mfma_f32_16x16x32_bf16 v[0:3], v[198:201], v[230:233], v[0:3]
	s_setprio 2
	s_barrier
	s_add_i32 s62, 0, 0x18000
	s_add_i32 s63, 0, 0x1c000
	v_add_u32_e32 v162, s62, v169
	v_add_u32_e32 v182, s63, v169
	ds_read_b128 v[142:145], v162
	ds_read_b128 v[146:149], v162 offset:1024
	ds_read_b128 v[150:153], v162 offset:2048
	ds_read_b128 v[162:165], v162 offset:3072
	ds_read_b128 v[186:189], v182
	ds_read_b128 v[190:193], v182 offset:1024
	ds_read_b128 v[194:197], v182 offset:2048
	ds_read_b128 v[198:201], v182 offset:3072
	s_add_u32 s36, s36, 0x40000
	s_addc_u32 s37, s37, 0
	s_mov_b32 m0, s45
	v_lshl_add_u64 v[182:183], s[36:37], 0, v[134:135]
	ds_read_b128 v[202:205], v173 offset:32768
	ds_read_b128 v[206:209], v173 offset:33792
	ds_read_b128 v[210:213], v173 offset:34816
	ds_read_b128 v[214:217], v173 offset:35840
	ds_read_b128 v[218:221], v173 offset:36864
	ds_read_b128 v[222:225], v173 offset:37888
	ds_read_b128 v[226:229], v173 offset:38912
	ds_read_b128 v[230:233], v173 offset:39936
	global_load_lds_dwordx4 v[182:183], off
	s_mov_b32 m0, s46
	v_lshl_add_u64 v[182:183], s[36:37], 0, v[132:133]
	global_load_lds_dwordx4 v[182:183], off
	s_setprio 1
	s_waitcnt vmcnt(8) lgkmcnt(0)
	s_barrier
	v_mfma_f32_16x16x32_bf16 v[126:129], v[142:145], v[202:205], v[126:129]
	v_mfma_f32_16x16x32_bf16 v[122:125], v[150:153], v[202:205], v[122:125]
	v_mfma_f32_16x16x32_bf16 v[110:113], v[142:145], v[210:213], v[110:113]
	v_mfma_f32_16x16x32_bf16 v[106:109], v[150:153], v[210:213], v[106:109]
	v_mfma_f32_16x16x32_bf16 v[92:95], v[142:145], v[218:221], v[92:95]
	v_mfma_f32_16x16x32_bf16 v[88:91], v[150:153], v[218:221], v[88:91]
	v_mfma_f32_16x16x32_bf16 v[76:79], v[142:145], v[226:229], v[76:79]
	v_mfma_f32_16x16x32_bf16 v[72:75], v[150:153], v[226:229], v[72:75]
	v_mfma_f32_16x16x32_bf16 v[126:129], v[146:149], v[206:209], v[126:129]
	v_mfma_f32_16x16x32_bf16 v[122:125], v[162:165], v[206:209], v[122:125]
	v_mfma_f32_16x16x32_bf16 v[110:113], v[146:149], v[214:217], v[110:113]
	v_mfma_f32_16x16x32_bf16 v[106:109], v[162:165], v[214:217], v[106:109]
	v_mfma_f32_16x16x32_bf16 v[92:95], v[146:149], v[222:225], v[92:95]
	v_mfma_f32_16x16x32_bf16 v[88:91], v[162:165], v[222:225], v[88:91]
	v_mfma_f32_16x16x32_bf16 v[76:79], v[146:149], v[230:233], v[76:79]
	v_mfma_f32_16x16x32_bf16 v[72:75], v[162:165], v[230:233], v[72:75]
	s_setprio 0
	s_setprio 1
	v_mfma_f32_16x16x32_bf16 v[118:121], v[186:189], v[202:205], v[118:121]
	v_mfma_f32_16x16x32_bf16 v[114:117], v[194:197], v[202:205], v[114:117]
	v_mfma_f32_16x16x32_bf16 v[102:105], v[186:189], v[210:213], v[102:105]
	v_mfma_f32_16x16x32_bf16 v[98:101], v[194:197], v[210:213], v[98:101]
	v_mfma_f32_16x16x32_bf16 v[84:87], v[186:189], v[218:221], v[84:87]
	v_mfma_f32_16x16x32_bf16 v[80:83], v[194:197], v[218:221], v[80:83]
	v_mfma_f32_16x16x32_bf16 v[68:71], v[186:189], v[226:229], v[68:71]
	v_mfma_f32_16x16x32_bf16 v[64:67], v[194:197], v[226:229], v[64:67]
	v_mfma_f32_16x16x32_bf16 v[118:121], v[190:193], v[206:209], v[118:121]
	v_mfma_f32_16x16x32_bf16 v[114:117], v[198:201], v[206:209], v[114:117]
	v_mfma_f32_16x16x32_bf16 v[102:105], v[190:193], v[214:217], v[102:105]
	v_mfma_f32_16x16x32_bf16 v[98:101], v[198:201], v[214:217], v[98:101]
	v_mfma_f32_16x16x32_bf16 v[84:87], v[190:193], v[222:225], v[84:87]
	v_mfma_f32_16x16x32_bf16 v[80:83], v[198:201], v[222:225], v[80:83]
	v_mfma_f32_16x16x32_bf16 v[68:71], v[190:193], v[230:233], v[68:71]
	v_mfma_f32_16x16x32_bf16 v[64:67], v[198:201], v[230:233], v[64:67]
	s_setprio 2
	s_barrier
	s_add_i32 s36, s62, s42
	v_lshl_add_u64 v[154:155], v[154:155], 0, s[16:17]
	s_mov_b32 m0, s36
	ds_read_b128 v[202:205], v173 offset:49152
	ds_read_b128 v[206:209], v173 offset:50176
	ds_read_b128 v[210:213], v173 offset:51200
	ds_read_b128 v[214:217], v173 offset:52224
	ds_read_b128 v[218:221], v173 offset:53248
	ds_read_b128 v[222:225], v173 offset:54272
	ds_read_b128 v[226:229], v173 offset:55296
	ds_read_b128 v[230:233], v173 offset:56320
	global_load_lds_dwordx4 v[154:155], off
	s_add_i32 m0, s36, 0x2000
	s_add_u32 s14, s14, 0x40080
	v_lshl_add_u64 v[154:155], v[156:157], 0, s[16:17]
	s_addc_u32 s15, s15, 0
	s_add_i32 s36, s63, s42
	global_load_lds_dwordx4 v[154:155], off
	s_mov_b32 m0, s36
	v_lshl_add_u64 v[154:155], s[14:15], 0, v[96:97]
	global_load_lds_dwordx4 v[154:155], off
	s_add_i32 m0, s36, 0x2000
	v_lshl_add_u64 v[154:155], s[14:15], 0, v[130:131]
	global_load_lds_dwordx4 v[154:155], off
	s_mov_b32 m0, s52
	v_lshl_add_u64 v[154:155], v[158:159], 0, s[16:17]
	global_load_lds_dwordx4 v[154:155], off
	s_mov_b32 m0, s53
	v_lshl_add_u64 v[154:155], v[166:167], 0, s[16:17]
	global_load_lds_dwordx4 v[154:155], off
	s_setprio 1
	s_waitcnt vmcnt(8) lgkmcnt(0)
	s_barrier
	v_mfma_f32_16x16x32_bf16 v[60:63], v[142:145], v[202:205], v[60:63]
	v_mfma_f32_16x16x32_bf16 v[56:59], v[150:153], v[202:205], v[56:59]
	v_mfma_f32_16x16x32_bf16 v[44:47], v[142:145], v[210:213], v[44:47]
	v_mfma_f32_16x16x32_bf16 v[40:43], v[150:153], v[210:213], v[40:43]
	v_mfma_f32_16x16x32_bf16 v[28:31], v[142:145], v[218:221], v[28:31]
	v_mfma_f32_16x16x32_bf16 v[24:27], v[150:153], v[218:221], v[24:27]
	v_mfma_f32_16x16x32_bf16 v[12:15], v[142:145], v[226:229], v[12:15]
	v_mfma_f32_16x16x32_bf16 v[8:11], v[150:153], v[226:229], v[8:11]
	v_mfma_f32_16x16x32_bf16 v[60:63], v[146:149], v[206:209], v[60:63]
	v_mfma_f32_16x16x32_bf16 v[56:59], v[162:165], v[206:209], v[56:59]
	v_mfma_f32_16x16x32_bf16 v[44:47], v[146:149], v[214:217], v[44:47]
	v_mfma_f32_16x16x32_bf16 v[40:43], v[162:165], v[214:217], v[40:43]
	v_mfma_f32_16x16x32_bf16 v[28:31], v[146:149], v[222:225], v[28:31]
	v_mfma_f32_16x16x32_bf16 v[24:27], v[162:165], v[222:225], v[24:27]
	v_mfma_f32_16x16x32_bf16 v[12:15], v[146:149], v[230:233], v[12:15]
	v_mfma_f32_16x16x32_bf16 v[8:11], v[162:165], v[230:233], v[8:11]
	s_setprio 0
	s_setprio 1
	v_mfma_f32_16x16x32_bf16 v[52:55], v[186:189], v[202:205], v[52:55]
	v_mfma_f32_16x16x32_bf16 v[48:51], v[194:197], v[202:205], v[48:51]
	v_mfma_f32_16x16x32_bf16 v[36:39], v[186:189], v[210:213], v[36:39]
	v_mfma_f32_16x16x32_bf16 v[32:35], v[194:197], v[210:213], v[32:35]
	v_mfma_f32_16x16x32_bf16 v[20:23], v[186:189], v[218:221], v[20:23]
	v_mfma_f32_16x16x32_bf16 v[16:19], v[194:197], v[218:221], v[16:19]
	v_mfma_f32_16x16x32_bf16 v[4:7], v[186:189], v[226:229], v[4:7]
	v_mfma_f32_16x16x32_bf16 v[0:3], v[194:197], v[226:229], v[0:3]
	v_mfma_f32_16x16x32_bf16 v[52:55], v[190:193], v[206:209], v[52:55]
	v_mfma_f32_16x16x32_bf16 v[48:51], v[198:201], v[206:209], v[48:51]
	v_mfma_f32_16x16x32_bf16 v[36:39], v[190:193], v[214:217], v[36:39]
	v_mfma_f32_16x16x32_bf16 v[32:35], v[198:201], v[214:217], v[32:35]
	v_mfma_f32_16x16x32_bf16 v[20:23], v[190:193], v[222:225], v[20:23]
	v_mfma_f32_16x16x32_bf16 v[16:19], v[198:201], v[222:225], v[16:19]
	v_mfma_f32_16x16x32_bf16 v[4:7], v[190:193], v[230:233], v[4:7]
	v_mfma_f32_16x16x32_bf16 v[0:3], v[198:201], v[230:233], v[0:3]
	s_setprio 2
	s_barrier
	s_add_i32 s61, s61, 2
	s_add_u32 s4, s4, 0x100
	s_addc_u32 s5, s5, 0
	s_add_u32 s59, s59, 0x100
	s_addc_u32 s60, s60, 0
	s_cmp_gt_u32 s61, 13
	s_cbranch_scc0 .LBB0_427
	s_and_b64 vcc, exec, s[24:25]
	s_cbranch_vccz .LBB0_430
	s_barrier

.LBB0_449:
	s_add_u32 s30, s14, 0xfffc0080
	s_addc_u32 s31, s15, -1
	s_add_i32 s60, 0, 0x10000
	s_cmp_eq_u32 s59, 12
	s_cselect_b32 s35, s25, s31
	s_cselect_b32 s34, s55, s30
	v_add_u32_e32 v96, s60, v151
	s_cselect_b32 s31, s13, s58
	s_cselect_b32 s30, s56, s57
	s_add_i32 s62, 0, 0x14000
	ds_read_b128 v[144:147], v96
	ds_read_b128 v[164:167], v96 offset:1024
	ds_read_b128 v[168:171], v96 offset:2048
	ds_read_b128 v[186:189], v96 offset:3072
	v_add_u32_e32 v96, s62, v151
	ds_read_b128 v[190:193], v96
	ds_read_b128 v[194:197], v96 offset:1024
	ds_read_b128 v[198:201], v96 offset:2048
	ds_read_b128 v[202:205], v96 offset:3072
	v_lshl_add_u64 v[148:149], s[14:15], 0, v[140:141]
	s_add_i32 m0, s41, 0xc000
	ds_read_b128 v[206:209], v163
	ds_read_b128 v[210:213], v163 offset:1024
	ds_read_b128 v[214:217], v163 offset:2048
	ds_read_b128 v[218:221], v163 offset:3072
	ds_read_b128 v[222:225], v163 offset:4096
	ds_read_b128 v[226:229], v163 offset:5120
	ds_read_b128 v[230:233], v163 offset:6144
	ds_read_b128 v[242:245], v163 offset:7168
	global_load_lds_dwordx4 v[148:149], off
	s_add_i32 m0, s41, 0xe000
	v_lshl_add_u64 v[148:149], s[14:15], 0, v[142:143]
	global_load_lds_dwordx4 v[148:149], off
	s_setprio 1
	s_waitcnt vmcnt(8) lgkmcnt(0)
	s_barrier
	v_mfma_f32_16x16x32_bf16 v[126:129], v[144:147], v[206:209], v[126:129]
	v_mfma_f32_16x16x32_bf16 v[122:125], v[168:171], v[206:209], v[122:125]
	v_mfma_f32_16x16x32_bf16 v[110:113], v[144:147], v[214:217], v[110:113]
	v_mfma_f32_16x16x32_bf16 v[106:109], v[168:171], v[214:217], v[106:109]
	v_mfma_f32_16x16x32_bf16 v[92:95], v[144:147], v[222:225], v[92:95]
	v_mfma_f32_16x16x32_bf16 v[88:91], v[168:171], v[222:225], v[88:91]
	v_mfma_f32_16x16x32_bf16 v[76:79], v[144:147], v[230:233], v[76:79]
	v_mfma_f32_16x16x32_bf16 v[72:75], v[168:171], v[230:233], v[72:75]
	v_mfma_f32_16x16x32_bf16 v[126:129], v[164:167], v[210:213], v[126:129]
	v_mfma_f32_16x16x32_bf16 v[122:125], v[186:189], v[210:213], v[122:125]
	v_mfma_f32_16x16x32_bf16 v[110:113], v[164:167], v[218:221], v[110:113]
	v_mfma_f32_16x16x32_bf16 v[106:109], v[186:189], v[218:221], v[106:109]
	v_mfma_f32_16x16x32_bf16 v[92:95], v[164:167], v[226:229], v[92:95]
	v_mfma_f32_16x16x32_bf16 v[88:91], v[186:189], v[226:229], v[88:91]
	v_mfma_f32_16x16x32_bf16 v[76:79], v[164:167], v[242:245], v[76:79]
	v_mfma_f32_16x16x32_bf16 v[72:75], v[186:189], v[242:245], v[72:75]
	s_setprio 0
	s_setprio 1
	v_mfma_f32_16x16x32_bf16 v[118:121], v[190:193], v[206:209], v[118:121]
	v_mfma_f32_16x16x32_bf16 v[114:117], v[198:201], v[206:209], v[114:117]
	v_mfma_f32_16x16x32_bf16 v[102:105], v[190:193], v[214:217], v[102:105]
	v_mfma_f32_16x16x32_bf16 v[98:101], v[198:201], v[214:217], v[98:101]
	v_mfma_f32_16x16x32_bf16 v[84:87], v[190:193], v[222:225], v[84:87]
	v_mfma_f32_16x16x32_bf16 v[80:83], v[198:201], v[222:225], v[80:83]
	v_mfma_f32_16x16x32_bf16 v[68:71], v[190:193], v[230:233], v[68:71]
	v_mfma_f32_16x16x32_bf16 v[64:67], v[198:201], v[230:233], v[64:67]
	v_mfma_f32_16x16x32_bf16 v[118:121], v[194:197], v[210:213], v[118:121]
	v_mfma_f32_16x16x32_bf16 v[114:117], v[202:205], v[210:213], v[114:117]
	v_mfma_f32_16x16x32_bf16 v[102:105], v[194:197], v[218:221], v[102:105]
	v_mfma_f32_16x16x32_bf16 v[98:101], v[202:205], v[218:221], v[98:101]
	v_mfma_f32_16x16x32_bf16 v[84:87], v[194:197], v[226:229], v[84:87]
	v_mfma_f32_16x16x32_bf16 v[80:83], v[202:205], v[226:229], v[80:83]
	v_mfma_f32_16x16x32_bf16 v[68:71], v[194:197], v[242:245], v[68:71]
	v_mfma_f32_16x16x32_bf16 v[64:67], v[202:205], v[242:245], v[64:67]
	s_setprio 2
	s_barrier
	s_add_i32 s60, s60, s40
	v_lshl_add_u64 v[148:149], s[30:31], 0, v[134:135]
	s_mov_b32 m0, s60
	ds_read_b128 v[206:209], v163 offset:16384
	ds_read_b128 v[210:213], v163 offset:17408
	ds_read_b128 v[214:217], v163 offset:18432
	ds_read_b128 v[218:221], v163 offset:19456
	ds_read_b128 v[222:225], v163 offset:20480
	ds_read_b128 v[226:229], v163 offset:21504
	ds_read_b128 v[230:233], v163 offset:22528
	ds_read_b128 v[242:245], v163 offset:23552
	global_load_lds_dwordx4 v[148:149], off
	s_add_i32 m0, s60, 0x2000
	s_add_u32 s60, s30, 0x40000
	v_lshl_add_u64 v[154:155], s[30:31], 0, v[130:131]
	s_addc_u32 s61, s31, 0
	s_add_i32 s62, s62, s40
	global_load_lds_dwordx4 v[154:155], off
	v_lshl_add_u64 v[156:157], s[60:61], 0, v[134:135]
	s_mov_b32 m0, s62
	v_lshl_add_u64 v[158:159], s[34:35], 0, v[132:133]
	global_load_lds_dwordx4 v[156:157], off
	s_add_i32 m0, s62, 0x2000
	v_lshl_add_u64 v[156:157], s[60:61], 0, v[130:131]
	global_load_lds_dwordx4 v[156:157], off
	s_mov_b32 m0, s41
	v_lshl_add_u64 v[156:157], s[34:35], 0, v[136:137]
	global_load_lds_dwordx4 v[156:157], off
	s_mov_b32 m0, s42
	s_nop 0
	global_load_lds_dwordx4 v[158:159], off
	s_setprio 1
	s_waitcnt vmcnt(8) lgkmcnt(0)
	s_barrier
	v_mfma_f32_16x16x32_bf16 v[60:63], v[144:147], v[206:209], v[60:63]
	v_mfma_f32_16x16x32_bf16 v[56:59], v[168:171], v[206:209], v[56:59]
	v_mfma_f32_16x16x32_bf16 v[44:47], v[144:147], v[214:217], v[44:47]
	v_mfma_f32_16x16x32_bf16 v[40:43], v[168:171], v[214:217], v[40:43]
	v_mfma_f32_16x16x32_bf16 v[28:31], v[144:147], v[222:225], v[28:31]
	v_mfma_f32_16x16x32_bf16 v[24:27], v[168:171], v[222:225], v[24:27]
	v_mfma_f32_16x16x32_bf16 v[12:15], v[144:147], v[230:233], v[12:15]
	v_mfma_f32_16x16x32_bf16 v[8:11], v[168:171], v[230:233], v[8:11]
	v_mfma_f32_16x16x32_bf16 v[60:63], v[164:167], v[210:213], v[60:63]
	v_mfma_f32_16x16x32_bf16 v[56:59], v[186:189], v[210:213], v[56:59]
	v_mfma_f32_16x16x32_bf16 v[44:47], v[164:167], v[218:221], v[44:47]
	v_mfma_f32_16x16x32_bf16 v[40:43], v[186:189], v[218:221], v[40:43]
	v_mfma_f32_16x16x32_bf16 v[28:31], v[164:167], v[226:229], v[28:31]
	v_mfma_f32_16x16x32_bf16 v[24:27], v[186:189], v[226:229], v[24:27]
	v_mfma_f32_16x16x32_bf16 v[12:15], v[164:167], v[242:245], v[12:15]
	v_mfma_f32_16x16x32_bf16 v[8:11], v[186:189], v[242:245], v[8:11]
	s_setprio 0
	s_setprio 1
	v_mfma_f32_16x16x32_bf16 v[52:55], v[190:193], v[206:209], v[52:55]
	v_mfma_f32_16x16x32_bf16 v[48:51], v[198:201], v[206:209], v[48:51]
	v_mfma_f32_16x16x32_bf16 v[36:39], v[190:193], v[214:217], v[36:39]
	v_mfma_f32_16x16x32_bf16 v[32:35], v[198:201], v[214:217], v[32:35]
	v_mfma_f32_16x16x32_bf16 v[20:23], v[190:193], v[222:225], v[20:23]
	v_mfma_f32_16x16x32_bf16 v[16:19], v[198:201], v[222:225], v[16:19]
	v_mfma_f32_16x16x32_bf16 v[4:7], v[190:193], v[230:233], v[4:7]
	v_mfma_f32_16x16x32_bf16 v[0:3], v[198:201], v[230:233], v[0:3]
	v_mfma_f32_16x16x32_bf16 v[52:55], v[194:197], v[210:213], v[52:55]
	v_mfma_f32_16x16x32_bf16 v[48:51], v[202:205], v[210:213], v[48:51]
	v_mfma_f32_16x16x32_bf16 v[36:39], v[194:197], v[218:221], v[36:39]
	v_mfma_f32_16x16x32_bf16 v[32:35], v[202:205], v[218:221], v[32:35]
	v_mfma_f32_16x16x32_bf16 v[20:23], v[194:197], v[226:229], v[20:23]
	v_mfma_f32_16x16x32_bf16 v[16:19], v[202:205], v[226:229], v[16:19]
	v_mfma_f32_16x16x32_bf16 v[4:7], v[194:197], v[242:245], v[4:7]
	v_mfma_f32_16x16x32_bf16 v[0:3], v[202:205], v[242:245], v[0:3]
	s_setprio 2
	s_barrier
	s_add_i32 s60, 0, 0x18000
	v_add_u32_e32 v96, s60, v151
	s_add_i32 s61, 0, 0x1c000
	ds_read_b128 v[144:147], v96
	ds_read_b128 v[164:167], v96 offset:1024
	ds_read_b128 v[168:171], v96 offset:2048
	ds_read_b128 v[186:189], v96 offset:3072
	v_add_u32_e32 v96, s61, v151
	ds_read_b128 v[190:193], v96
	ds_read_b128 v[194:197], v96 offset:1024
	ds_read_b128 v[198:201], v96 offset:2048
	ds_read_b128 v[202:205], v96 offset:3072
	s_add_u32 s34, s34, 0x40000
	s_addc_u32 s35, s35, 0
	s_mov_b32 m0, s43
	v_lshl_add_u64 v[172:173], s[34:35], 0, v[136:137]
	ds_read_b128 v[206:209], v163 offset:32768
	ds_read_b128 v[210:213], v163 offset:33792
	ds_read_b128 v[214:217], v163 offset:34816
	ds_read_b128 v[218:221], v163 offset:35840
	ds_read_b128 v[222:225], v163 offset:36864
	ds_read_b128 v[226:229], v163 offset:37888
	ds_read_b128 v[230:233], v163 offset:38912
	ds_read_b128 v[242:245], v163 offset:39936
	global_load_lds_dwordx4 v[172:173], off
	s_mov_b32 m0, s44
	v_lshl_add_u64 v[172:173], s[34:35], 0, v[132:133]
	global_load_lds_dwordx4 v[172:173], off
	s_setprio 1
	s_waitcnt vmcnt(8) lgkmcnt(0)
	s_barrier
	v_mfma_f32_16x16x32_bf16 v[126:129], v[144:147], v[206:209], v[126:129]
	v_mfma_f32_16x16x32_bf16 v[122:125], v[168:171], v[206:209], v[122:125]
	v_mfma_f32_16x16x32_bf16 v[110:113], v[144:147], v[214:217], v[110:113]
	v_mfma_f32_16x16x32_bf16 v[106:109], v[168:171], v[214:217], v[106:109]
	v_mfma_f32_16x16x32_bf16 v[92:95], v[144:147], v[222:225], v[92:95]
	v_mfma_f32_16x16x32_bf16 v[88:91], v[168:171], v[222:225], v[88:91]
	v_mfma_f32_16x16x32_bf16 v[76:79], v[144:147], v[230:233], v[76:79]
	v_mfma_f32_16x16x32_bf16 v[72:75], v[168:171], v[230:233], v[72:75]
	v_mfma_f32_16x16x32_bf16 v[126:129], v[164:167], v[210:213], v[126:129]
	v_mfma_f32_16x16x32_bf16 v[122:125], v[186:189], v[210:213], v[122:125]
	v_mfma_f32_16x16x32_bf16 v[110:113], v[164:167], v[218:221], v[110:113]
	v_mfma_f32_16x16x32_bf16 v[106:109], v[186:189], v[218:221], v[106:109]
	v_mfma_f32_16x16x32_bf16 v[92:95], v[164:167], v[226:229], v[92:95]
	v_mfma_f32_16x16x32_bf16 v[88:91], v[186:189], v[226:229], v[88:91]
	v_mfma_f32_16x16x32_bf16 v[76:79], v[164:167], v[242:245], v[76:79]
	v_mfma_f32_16x16x32_bf16 v[72:75], v[186:189], v[242:245], v[72:75]
	s_setprio 0
	s_setprio 1
	v_mfma_f32_16x16x32_bf16 v[118:121], v[190:193], v[206:209], v[118:121]
	v_mfma_f32_16x16x32_bf16 v[114:117], v[198:201], v[206:209], v[114:117]
	v_mfma_f32_16x16x32_bf16 v[102:105], v[190:193], v[214:217], v[102:105]
	v_mfma_f32_16x16x32_bf16 v[98:101], v[198:201], v[214:217], v[98:101]
	v_mfma_f32_16x16x32_bf16 v[84:87], v[190:193], v[222:225], v[84:87]
	v_mfma_f32_16x16x32_bf16 v[80:83], v[198:201], v[222:225], v[80:83]
	v_mfma_f32_16x16x32_bf16 v[68:71], v[190:193], v[230:233], v[68:71]
	v_mfma_f32_16x16x32_bf16 v[64:67], v[198:201], v[230:233], v[64:67]
	v_mfma_f32_16x16x32_bf16 v[118:121], v[194:197], v[210:213], v[118:121]
	v_mfma_f32_16x16x32_bf16 v[114:117], v[202:205], v[210:213], v[114:117]
	v_mfma_f32_16x16x32_bf16 v[102:105], v[194:197], v[218:221], v[102:105]
	v_mfma_f32_16x16x32_bf16 v[98:101], v[202:205], v[218:221], v[98:101]
	v_mfma_f32_16x16x32_bf16 v[84:87], v[194:197], v[226:229], v[84:87]
	v_mfma_f32_16x16x32_bf16 v[80:83], v[202:205], v[226:229], v[80:83]
	v_mfma_f32_16x16x32_bf16 v[68:71], v[194:197], v[242:245], v[68:71]
	v_mfma_f32_16x16x32_bf16 v[64:67], v[202:205], v[242:245], v[64:67]
	s_setprio 2
	s_barrier
	s_add_i32 s34, s60, s40
	v_lshl_add_u64 v[148:149], v[148:149], 0, s[16:17]
	s_mov_b32 m0, s34
	ds_read_b128 v[206:209], v163 offset:49152
	ds_read_b128 v[210:213], v163 offset:50176
	ds_read_b128 v[214:217], v163 offset:51200
	ds_read_b128 v[218:221], v163 offset:52224
	ds_read_b128 v[222:225], v163 offset:53248
	ds_read_b128 v[226:229], v163 offset:54272
	ds_read_b128 v[230:233], v163 offset:55296
	ds_read_b128 v[242:245], v163 offset:56320
	global_load_lds_dwordx4 v[148:149], off
	s_add_i32 m0, s34, 0x2000
	s_add_u32 s30, s30, 0x40080
	v_lshl_add_u64 v[148:149], v[154:155], 0, s[16:17]
	s_addc_u32 s31, s31, 0
	s_add_i32 s34, s61, s40
	global_load_lds_dwordx4 v[148:149], off
	s_mov_b32 m0, s34
	v_lshl_add_u64 v[148:149], s[30:31], 0, v[134:135]
	global_load_lds_dwordx4 v[148:149], off
	s_add_i32 m0, s34, 0x2000
	v_lshl_add_u64 v[148:149], s[30:31], 0, v[130:131]
	global_load_lds_dwordx4 v[148:149], off
	s_mov_b32 m0, s49
	v_lshl_add_u64 v[148:149], v[156:157], 0, s[16:17]
	global_load_lds_dwordx4 v[148:149], off
	s_mov_b32 m0, s50
	v_lshl_add_u64 v[148:149], v[158:159], 0, s[16:17]
	global_load_lds_dwordx4 v[148:149], off
	s_setprio 1
	s_waitcnt vmcnt(8) lgkmcnt(0)
	s_barrier
	v_mfma_f32_16x16x32_bf16 v[60:63], v[144:147], v[206:209], v[60:63]
	v_mfma_f32_16x16x32_bf16 v[56:59], v[168:171], v[206:209], v[56:59]
	v_mfma_f32_16x16x32_bf16 v[44:47], v[144:147], v[214:217], v[44:47]
	v_mfma_f32_16x16x32_bf16 v[40:43], v[168:171], v[214:217], v[40:43]
	v_mfma_f32_16x16x32_bf16 v[28:31], v[144:147], v[222:225], v[28:31]
	v_mfma_f32_16x16x32_bf16 v[24:27], v[168:171], v[222:225], v[24:27]
	v_mfma_f32_16x16x32_bf16 v[12:15], v[144:147], v[230:233], v[12:15]
	v_mfma_f32_16x16x32_bf16 v[8:11], v[168:171], v[230:233], v[8:11]
	v_mfma_f32_16x16x32_bf16 v[60:63], v[164:167], v[210:213], v[60:63]
	v_mfma_f32_16x16x32_bf16 v[56:59], v[186:189], v[210:213], v[56:59]
	v_mfma_f32_16x16x32_bf16 v[44:47], v[164:167], v[218:221], v[44:47]
	v_mfma_f32_16x16x32_bf16 v[40:43], v[186:189], v[218:221], v[40:43]
	v_mfma_f32_16x16x32_bf16 v[28:31], v[164:167], v[226:229], v[28:31]
	v_mfma_f32_16x16x32_bf16 v[24:27], v[186:189], v[226:229], v[24:27]
	v_mfma_f32_16x16x32_bf16 v[12:15], v[164:167], v[242:245], v[12:15]
	v_mfma_f32_16x16x32_bf16 v[8:11], v[186:189], v[242:245], v[8:11]
	s_setprio 0
	s_setprio 1
	v_mfma_f32_16x16x32_bf16 v[52:55], v[190:193], v[206:209], v[52:55]
	v_mfma_f32_16x16x32_bf16 v[48:51], v[198:201], v[206:209], v[48:51]
	v_mfma_f32_16x16x32_bf16 v[36:39], v[190:193], v[214:217], v[36:39]
	v_mfma_f32_16x16x32_bf16 v[32:35], v[198:201], v[214:217], v[32:35]
	v_mfma_f32_16x16x32_bf16 v[20:23], v[190:193], v[222:225], v[20:23]
	v_mfma_f32_16x16x32_bf16 v[16:19], v[198:201], v[222:225], v[16:19]
	v_mfma_f32_16x16x32_bf16 v[4:7], v[190:193], v[230:233], v[4:7]
	v_mfma_f32_16x16x32_bf16 v[0:3], v[198:201], v[230:233], v[0:3]
	v_mfma_f32_16x16x32_bf16 v[52:55], v[194:197], v[210:213], v[52:55]
	v_mfma_f32_16x16x32_bf16 v[48:51], v[202:205], v[210:213], v[48:51]
	v_mfma_f32_16x16x32_bf16 v[36:39], v[194:197], v[218:221], v[36:39]
	v_mfma_f32_16x16x32_bf16 v[32:35], v[202:205], v[218:221], v[32:35]
	v_mfma_f32_16x16x32_bf16 v[20:23], v[194:197], v[226:229], v[20:23]
	v_mfma_f32_16x16x32_bf16 v[16:19], v[202:205], v[226:229], v[16:19]
	v_mfma_f32_16x16x32_bf16 v[4:7], v[194:197], v[242:245], v[4:7]
	v_mfma_f32_16x16x32_bf16 v[0:3], v[202:205], v[242:245], v[0:3]
	s_setprio 2
	s_barrier
	s_add_i32 s59, s59, 2
	s_add_u32 s14, s14, 0x100
	s_addc_u32 s15, s15, 0
	s_add_u32 s57, s57, 0x100
	s_addc_u32 s58, s58, 0
	s_cmp_gt_u32 s59, 13
	s_cbranch_scc0 .LBB0_449
	s_and_b64 vcc, exec, s[18:19]
	s_cbranch_vccz .LBB0_454
	s_barrier
	v_lshl_add_u32 v146, s54, 8, v150
	s_cmp_gt_i32 s53, 7
	s_mov_b64 s[14:15], -1
	s_cbranch_scc1 .LBB0_455

.LBB0_490:
	s_add_i32 s66, s6, 2
	s_add_u32 s67, s4, 0x80
	s_addc_u32 s7, s5, 0
	s_add_i32 s70, 0, 0x10000
	s_cmp_eq_u32 s60, s6
	s_cselect_b32 s7, s43, s7
	s_cselect_b32 s6, s42, s67
	v_add_u32_e32 v148, s70, v151
	s_cselect_b32 s69, s45, s15
	s_cselect_b32 s68, s44, s14
	s_add_i32 s67, 0, 0x14000
	ds_read_b128 v[140:143], v148
	ds_read_b128 v[144:147], v148 offset:1024
	ds_read_b128 v[162:165], v148 offset:2048
	ds_read_b128 v[166:169], v148 offset:3072
	v_add_u32_e32 v148, s67, v151
	ds_read_b128 v[170:173], v148
	ds_read_b128 v[186:189], v148 offset:1024
	ds_read_b128 v[190:193], v148 offset:2048
	ds_read_b128 v[194:197], v148 offset:3072
	v_lshl_add_u64 v[148:149], s[4:5], 0, v[136:137]
	s_add_i32 m0, s52, 0xc000
	ds_read_b128 v[198:201], v153
	ds_read_b128 v[202:205], v153 offset:1024
	ds_read_b128 v[206:209], v153 offset:2048
	ds_read_b128 v[210:213], v153 offset:3072
	ds_read_b128 v[214:217], v153 offset:4096
	ds_read_b128 v[218:221], v153 offset:5120
	ds_read_b128 v[222:225], v153 offset:6144
	ds_read_b128 v[226:229], v153 offset:7168
	global_load_lds_dwordx4 v[148:149], off
	s_add_i32 m0, s52, 0xe000
	v_lshl_add_u64 v[148:149], s[4:5], 0, v[138:139]
	global_load_lds_dwordx4 v[148:149], off
	s_setprio 1
	s_waitcnt vmcnt(8) lgkmcnt(0)
	s_barrier
	v_mfma_f32_16x16x32_bf16 v[126:129], v[140:143], v[198:201], v[126:129]
	v_mfma_f32_16x16x32_bf16 v[122:125], v[162:165], v[198:201], v[122:125]
	v_mfma_f32_16x16x32_bf16 v[110:113], v[140:143], v[206:209], v[110:113]
	v_mfma_f32_16x16x32_bf16 v[106:109], v[162:165], v[206:209], v[106:109]
	v_mfma_f32_16x16x32_bf16 v[92:95], v[140:143], v[214:217], v[92:95]
	v_mfma_f32_16x16x32_bf16 v[88:91], v[162:165], v[214:217], v[88:91]
	v_mfma_f32_16x16x32_bf16 v[76:79], v[140:143], v[222:225], v[76:79]
	v_mfma_f32_16x16x32_bf16 v[72:75], v[162:165], v[222:225], v[72:75]
	v_mfma_f32_16x16x32_bf16 v[126:129], v[144:147], v[202:205], v[126:129]
	v_mfma_f32_16x16x32_bf16 v[122:125], v[166:169], v[202:205], v[122:125]
	v_mfma_f32_16x16x32_bf16 v[110:113], v[144:147], v[210:213], v[110:113]
	v_mfma_f32_16x16x32_bf16 v[106:109], v[166:169], v[210:213], v[106:109]
	v_mfma_f32_16x16x32_bf16 v[92:95], v[144:147], v[218:221], v[92:95]
	v_mfma_f32_16x16x32_bf16 v[88:91], v[166:169], v[218:221], v[88:91]
	v_mfma_f32_16x16x32_bf16 v[76:79], v[144:147], v[226:229], v[76:79]
	v_mfma_f32_16x16x32_bf16 v[72:75], v[166:169], v[226:229], v[72:75]
	s_setprio 0
	s_setprio 1
	v_mfma_f32_16x16x32_bf16 v[118:121], v[170:173], v[198:201], v[118:121]
	v_mfma_f32_16x16x32_bf16 v[114:117], v[190:193], v[198:201], v[114:117]
	v_mfma_f32_16x16x32_bf16 v[102:105], v[170:173], v[206:209], v[102:105]
	v_mfma_f32_16x16x32_bf16 v[98:101], v[190:193], v[206:209], v[98:101]
	v_mfma_f32_16x16x32_bf16 v[84:87], v[170:173], v[214:217], v[84:87]
	v_mfma_f32_16x16x32_bf16 v[80:83], v[190:193], v[214:217], v[80:83]
	v_mfma_f32_16x16x32_bf16 v[68:71], v[170:173], v[222:225], v[68:71]
	v_mfma_f32_16x16x32_bf16 v[64:67], v[190:193], v[222:225], v[64:67]
	v_mfma_f32_16x16x32_bf16 v[118:121], v[186:189], v[202:205], v[118:121]
	v_mfma_f32_16x16x32_bf16 v[114:117], v[194:197], v[202:205], v[114:117]
	v_mfma_f32_16x16x32_bf16 v[102:105], v[186:189], v[210:213], v[102:105]
	v_mfma_f32_16x16x32_bf16 v[98:101], v[194:197], v[210:213], v[98:101]
	v_mfma_f32_16x16x32_bf16 v[84:87], v[186:189], v[218:221], v[84:87]
	v_mfma_f32_16x16x32_bf16 v[80:83], v[194:197], v[218:221], v[80:83]
	v_mfma_f32_16x16x32_bf16 v[68:71], v[186:189], v[226:229], v[68:71]
	v_mfma_f32_16x16x32_bf16 v[64:67], v[194:197], v[226:229], v[64:67]
	s_setprio 2
	s_barrier
	s_add_i32 s70, s70, s51
	v_lshl_add_u64 v[148:149], s[68:69], 0, v[96:97]
	s_mov_b32 m0, s70
	ds_read_b128 v[198:201], v153 offset:16384
	ds_read_b128 v[202:205], v153 offset:17408
	ds_read_b128 v[206:209], v153 offset:18432
	ds_read_b128 v[210:213], v153 offset:19456
	ds_read_b128 v[214:217], v153 offset:20480
	ds_read_b128 v[218:221], v153 offset:21504
	ds_read_b128 v[222:225], v153 offset:22528
	ds_read_b128 v[226:229], v153 offset:23552
	global_load_lds_dwordx4 v[148:149], off
	s_add_i32 m0, s70, 0x2000
	v_lshl_add_u64 v[154:155], s[68:69], 0, v[130:131]
	s_add_u32 s68, s68, s46
	s_addc_u32 s69, s69, 0
	s_add_i32 s67, s67, s51
	global_load_lds_dwordx4 v[154:155], off
	v_lshl_add_u64 v[156:157], s[68:69], 0, v[96:97]
	s_mov_b32 m0, s67
	v_lshl_add_u64 v[158:159], s[68:69], 0, v[130:131]
	global_load_lds_dwordx4 v[156:157], off
	s_add_i32 m0, s67, 0x2000
	v_lshl_add_u64 v[182:183], s[6:7], 0, v[134:135]
	global_load_lds_dwordx4 v[158:159], off
	s_mov_b32 m0, s52
	v_lshl_add_u64 v[184:185], s[6:7], 0, v[132:133]
	global_load_lds_dwordx4 v[182:183], off
	s_mov_b32 m0, s53
	s_nop 0
	global_load_lds_dwordx4 v[184:185], off
	s_setprio 1
	s_waitcnt vmcnt(8) lgkmcnt(0)
	s_barrier
	v_mfma_f32_16x16x32_bf16 v[60:63], v[140:143], v[198:201], v[60:63]
	v_mfma_f32_16x16x32_bf16 v[56:59], v[162:165], v[198:201], v[56:59]
	v_mfma_f32_16x16x32_bf16 v[44:47], v[140:143], v[206:209], v[44:47]
	v_mfma_f32_16x16x32_bf16 v[40:43], v[162:165], v[206:209], v[40:43]
	v_mfma_f32_16x16x32_bf16 v[28:31], v[140:143], v[214:217], v[28:31]
	v_mfma_f32_16x16x32_bf16 v[24:27], v[162:165], v[214:217], v[24:27]
	v_mfma_f32_16x16x32_bf16 v[12:15], v[140:143], v[222:225], v[12:15]
	v_mfma_f32_16x16x32_bf16 v[8:11], v[162:165], v[222:225], v[8:11]
	v_mfma_f32_16x16x32_bf16 v[60:63], v[144:147], v[202:205], v[60:63]
	v_mfma_f32_16x16x32_bf16 v[56:59], v[166:169], v[202:205], v[56:59]
	v_mfma_f32_16x16x32_bf16 v[44:47], v[144:147], v[210:213], v[44:47]
	v_mfma_f32_16x16x32_bf16 v[40:43], v[166:169], v[210:213], v[40:43]
	v_mfma_f32_16x16x32_bf16 v[28:31], v[144:147], v[218:221], v[28:31]
	v_mfma_f32_16x16x32_bf16 v[24:27], v[166:169], v[218:221], v[24:27]
	v_mfma_f32_16x16x32_bf16 v[12:15], v[144:147], v[226:229], v[12:15]
	v_mfma_f32_16x16x32_bf16 v[8:11], v[166:169], v[226:229], v[8:11]
	s_setprio 0
	s_setprio 1
	v_mfma_f32_16x16x32_bf16 v[52:55], v[170:173], v[198:201], v[52:55]
	v_mfma_f32_16x16x32_bf16 v[48:51], v[190:193], v[198:201], v[48:51]
	v_mfma_f32_16x16x32_bf16 v[36:39], v[170:173], v[206:209], v[36:39]
	v_mfma_f32_16x16x32_bf16 v[32:35], v[190:193], v[206:209], v[32:35]
	v_mfma_f32_16x16x32_bf16 v[20:23], v[170:173], v[214:217], v[20:23]
	v_mfma_f32_16x16x32_bf16 v[16:19], v[190:193], v[214:217], v[16:19]
	v_mfma_f32_16x16x32_bf16 v[4:7], v[170:173], v[222:225], v[4:7]
	v_mfma_f32_16x16x32_bf16 v[0:3], v[190:193], v[222:225], v[0:3]
	v_mfma_f32_16x16x32_bf16 v[52:55], v[186:189], v[202:205], v[52:55]
	v_mfma_f32_16x16x32_bf16 v[48:51], v[194:197], v[202:205], v[48:51]
	v_mfma_f32_16x16x32_bf16 v[36:39], v[186:189], v[210:213], v[36:39]
	v_mfma_f32_16x16x32_bf16 v[32:35], v[194:197], v[210:213], v[32:35]
	v_mfma_f32_16x16x32_bf16 v[20:23], v[186:189], v[218:221], v[20:23]
	v_mfma_f32_16x16x32_bf16 v[16:19], v[194:197], v[218:221], v[16:19]
	v_mfma_f32_16x16x32_bf16 v[4:7], v[186:189], v[226:229], v[4:7]
	v_mfma_f32_16x16x32_bf16 v[0:3], v[194:197], v[226:229], v[0:3]
	s_setprio 2
	s_barrier
	s_add_i32 s67, 0, 0x18000
	s_add_i32 s68, 0, 0x1c000
	v_add_u32_e32 v166, s67, v151
	v_add_u32_e32 v194, s68, v151
	ds_read_b128 v[140:143], v166
	ds_read_b128 v[144:147], v166 offset:1024
	ds_read_b128 v[162:165], v166 offset:2048
	ds_read_b128 v[166:169], v166 offset:3072
	ds_read_b128 v[170:173], v194
	ds_read_b128 v[186:189], v194 offset:1024
	ds_read_b128 v[190:193], v194 offset:2048
	ds_read_b128 v[194:197], v194 offset:3072
	s_add_u32 s6, s6, s46
	s_addc_u32 s7, s7, 0
	s_mov_b32 m0, s54
	v_lshl_add_u64 v[230:231], s[6:7], 0, v[134:135]
	ds_read_b128 v[198:201], v153 offset:32768
	ds_read_b128 v[202:205], v153 offset:33792
	ds_read_b128 v[206:209], v153 offset:34816
	ds_read_b128 v[210:213], v153 offset:35840
	ds_read_b128 v[214:217], v153 offset:36864
	ds_read_b128 v[218:221], v153 offset:37888
	ds_read_b128 v[222:225], v153 offset:38912
	ds_read_b128 v[226:229], v153 offset:39936
	global_load_lds_dwordx4 v[230:231], off
	s_mov_b32 m0, s55
	v_lshl_add_u64 v[230:231], s[6:7], 0, v[132:133]
	global_load_lds_dwordx4 v[230:231], off
	s_setprio 1
	s_waitcnt vmcnt(8) lgkmcnt(0)
	s_barrier
	v_mfma_f32_16x16x32_bf16 v[126:129], v[140:143], v[198:201], v[126:129]
	v_mfma_f32_16x16x32_bf16 v[122:125], v[162:165], v[198:201], v[122:125]
	v_mfma_f32_16x16x32_bf16 v[110:113], v[140:143], v[206:209], v[110:113]
	v_mfma_f32_16x16x32_bf16 v[106:109], v[162:165], v[206:209], v[106:109]
	v_mfma_f32_16x16x32_bf16 v[92:95], v[140:143], v[214:217], v[92:95]
	v_mfma_f32_16x16x32_bf16 v[88:91], v[162:165], v[214:217], v[88:91]
	v_mfma_f32_16x16x32_bf16 v[76:79], v[140:143], v[222:225], v[76:79]
	v_mfma_f32_16x16x32_bf16 v[72:75], v[162:165], v[222:225], v[72:75]
	v_mfma_f32_16x16x32_bf16 v[126:129], v[144:147], v[202:205], v[126:129]
	v_mfma_f32_16x16x32_bf16 v[122:125], v[166:169], v[202:205], v[122:125]
	v_mfma_f32_16x16x32_bf16 v[110:113], v[144:147], v[210:213], v[110:113]
	v_mfma_f32_16x16x32_bf16 v[106:109], v[166:169], v[210:213], v[106:109]
	v_mfma_f32_16x16x32_bf16 v[92:95], v[144:147], v[218:221], v[92:95]
	v_mfma_f32_16x16x32_bf16 v[88:91], v[166:169], v[218:221], v[88:91]
	v_mfma_f32_16x16x32_bf16 v[76:79], v[144:147], v[226:229], v[76:79]
	v_mfma_f32_16x16x32_bf16 v[72:75], v[166:169], v[226:229], v[72:75]
	s_setprio 0
	s_setprio 1
	v_mfma_f32_16x16x32_bf16 v[118:121], v[170:173], v[198:201], v[118:121]
	v_mfma_f32_16x16x32_bf16 v[114:117], v[190:193], v[198:201], v[114:117]
	v_mfma_f32_16x16x32_bf16 v[102:105], v[170:173], v[206:209], v[102:105]
	v_mfma_f32_16x16x32_bf16 v[98:101], v[190:193], v[206:209], v[98:101]
	v_mfma_f32_16x16x32_bf16 v[84:87], v[170:173], v[214:217], v[84:87]
	v_mfma_f32_16x16x32_bf16 v[80:83], v[190:193], v[214:217], v[80:83]
	v_mfma_f32_16x16x32_bf16 v[68:71], v[170:173], v[222:225], v[68:71]
	v_mfma_f32_16x16x32_bf16 v[64:67], v[190:193], v[222:225], v[64:67]
	v_mfma_f32_16x16x32_bf16 v[118:121], v[186:189], v[202:205], v[118:121]
	v_mfma_f32_16x16x32_bf16 v[114:117], v[194:197], v[202:205], v[114:117]
	v_mfma_f32_16x16x32_bf16 v[102:105], v[186:189], v[210:213], v[102:105]
	v_mfma_f32_16x16x32_bf16 v[98:101], v[194:197], v[210:213], v[98:101]
	v_mfma_f32_16x16x32_bf16 v[84:87], v[186:189], v[218:221], v[84:87]
	v_mfma_f32_16x16x32_bf16 v[80:83], v[194:197], v[218:221], v[80:83]
	v_mfma_f32_16x16x32_bf16 v[68:71], v[186:189], v[226:229], v[68:71]
	v_mfma_f32_16x16x32_bf16 v[64:67], v[194:197], v[226:229], v[64:67]
	s_setprio 2
	s_barrier
	s_add_i32 s6, s67, s51
	v_lshl_add_u64 v[148:149], v[148:149], 0, s[16:17]
	s_mov_b32 m0, s6
	ds_read_b128 v[198:201], v153 offset:49152
	ds_read_b128 v[202:205], v153 offset:50176
	ds_read_b128 v[206:209], v153 offset:51200
	ds_read_b128 v[210:213], v153 offset:52224
	ds_read_b128 v[214:217], v153 offset:53248
	ds_read_b128 v[218:221], v153 offset:54272
	ds_read_b128 v[222:225], v153 offset:55296
	ds_read_b128 v[226:229], v153 offset:56320
	global_load_lds_dwordx4 v[148:149], off
	v_lshl_add_u64 v[148:149], v[154:155], 0, s[16:17]
	s_add_i32 m0, s6, 0x2000
	s_add_i32 s6, s68, s51
	global_load_lds_dwordx4 v[148:149], off
	s_mov_b32 m0, s6
	v_lshl_add_u64 v[148:149], v[156:157], 0, s[16:17]
	global_load_lds_dwordx4 v[148:149], off
	s_add_i32 m0, s6, 0x2000
	v_lshl_add_u64 v[148:149], v[158:159], 0, s[16:17]
	global_load_lds_dwordx4 v[148:149], off
	s_mov_b32 m0, s56
	v_lshl_add_u64 v[148:149], v[182:183], 0, s[16:17]
	global_load_lds_dwordx4 v[148:149], off
	s_mov_b32 m0, s57
	v_lshl_add_u64 v[148:149], v[184:185], 0, s[16:17]
	global_load_lds_dwordx4 v[148:149], off
	s_setprio 1
	s_waitcnt vmcnt(8) lgkmcnt(0)
	s_barrier
	v_mfma_f32_16x16x32_bf16 v[60:63], v[140:143], v[198:201], v[60:63]
	v_mfma_f32_16x16x32_bf16 v[56:59], v[162:165], v[198:201], v[56:59]
	v_mfma_f32_16x16x32_bf16 v[44:47], v[140:143], v[206:209], v[44:47]
	v_mfma_f32_16x16x32_bf16 v[40:43], v[162:165], v[206:209], v[40:43]
	v_mfma_f32_16x16x32_bf16 v[28:31], v[140:143], v[214:217], v[28:31]
	v_mfma_f32_16x16x32_bf16 v[24:27], v[162:165], v[214:217], v[24:27]
	v_mfma_f32_16x16x32_bf16 v[12:15], v[140:143], v[222:225], v[12:15]
	v_mfma_f32_16x16x32_bf16 v[8:11], v[162:165], v[222:225], v[8:11]
	v_mfma_f32_16x16x32_bf16 v[60:63], v[144:147], v[202:205], v[60:63]
	v_mfma_f32_16x16x32_bf16 v[56:59], v[166:169], v[202:205], v[56:59]
	v_mfma_f32_16x16x32_bf16 v[44:47], v[144:147], v[210:213], v[44:47]
	v_mfma_f32_16x16x32_bf16 v[40:43], v[166:169], v[210:213], v[40:43]
	v_mfma_f32_16x16x32_bf16 v[28:31], v[144:147], v[218:221], v[28:31]
	v_mfma_f32_16x16x32_bf16 v[24:27], v[166:169], v[218:221], v[24:27]
	v_mfma_f32_16x16x32_bf16 v[12:15], v[144:147], v[226:229], v[12:15]
	v_mfma_f32_16x16x32_bf16 v[8:11], v[166:169], v[226:229], v[8:11]
	s_setprio 0
	s_setprio 1
	v_mfma_f32_16x16x32_bf16 v[52:55], v[170:173], v[198:201], v[52:55]
	v_mfma_f32_16x16x32_bf16 v[48:51], v[190:193], v[198:201], v[48:51]
	v_mfma_f32_16x16x32_bf16 v[36:39], v[170:173], v[206:209], v[36:39]
	v_mfma_f32_16x16x32_bf16 v[32:35], v[190:193], v[206:209], v[32:35]
	v_mfma_f32_16x16x32_bf16 v[20:23], v[170:173], v[214:217], v[20:23]
	v_mfma_f32_16x16x32_bf16 v[16:19], v[190:193], v[214:217], v[16:19]
	v_mfma_f32_16x16x32_bf16 v[4:7], v[170:173], v[222:225], v[4:7]
	v_mfma_f32_16x16x32_bf16 v[0:3], v[190:193], v[222:225], v[0:3]
	v_mfma_f32_16x16x32_bf16 v[52:55], v[186:189], v[202:205], v[52:55]
	v_mfma_f32_16x16x32_bf16 v[48:51], v[194:197], v[202:205], v[48:51]
	v_mfma_f32_16x16x32_bf16 v[36:39], v[186:189], v[210:213], v[36:39]
	v_mfma_f32_16x16x32_bf16 v[32:35], v[194:197], v[210:213], v[32:35]
	v_mfma_f32_16x16x32_bf16 v[20:23], v[186:189], v[218:221], v[20:23]
	v_mfma_f32_16x16x32_bf16 v[16:19], v[194:197], v[218:221], v[16:19]
	v_mfma_f32_16x16x32_bf16 v[4:7], v[186:189], v[226:229], v[4:7]
	v_mfma_f32_16x16x32_bf16 v[0:3], v[194:197], v[226:229], v[0:3]
	s_setprio 2
	s_barrier
	s_add_u32 s4, s4, 0x100
	s_addc_u32 s5, s5, 0
	s_add_u32 s14, s14, 0x100
	s_addc_u32 s15, s15, 0
	s_cmp_ge_u32 s66, s59
	s_mov_b32 s6, s66
	s_cbranch_scc0 .LBB0_490
	s_and_b64 vcc, exec, s[36:37]
	s_cbranch_vccz .LBB0_493
	s_barrier
